# K-loops: removed the redundant lgkmcnt(0) wait after each segment barrier (the same wait already precedes the barrier)
# baseline (speedup 1.0000x reference)
.LBB0_341:
	s_add_u32 s36, s34, 0xfffc0080
	s_addc_u32 s37, s35, -1
	s_add_i32 s56, 0, 0x10000
	s_cmp_eq_u32 s79, 12
	s_cselect_b32 s39, s25, s37
	s_cselect_b32 s38, s31, s36
	s_cselect_b32 s37, s23, s78
	s_cselect_b32 s36, s40, s77
	s_add_i32 s80, 0, 0x14000
	v_add_u32_e32 v102, s56, v171
	v_add_u32_e32 v177, s80, v171
	ds_read_b128 v[82:85], v102
	ds_read_b128 v[86:89], v102 offset:1024
	ds_read_b128 v[94:97], v102 offset:2048
	ds_read_b128 v[102:105], v102 offset:3072
	ds_read_b128 v[134:137], v177
	ds_read_b128 v[162:165], v177 offset:1024
	ds_read_b128 v[166:169], v177 offset:2048
	ds_read_b128 v[178:181], v177 offset:3072
	v_lshl_add_u64 v[214:215], s[34:35], 0, v[158:159]
	s_add_i32 m0, s9, 0xc000
	ds_read_b128 v[182:185], v176
	ds_read_b128 v[186:189], v176 offset:1024
	ds_read_b128 v[190:193], v176 offset:2048
	ds_read_b128 v[194:197], v176 offset:3072
	ds_read_b128 v[198:201], v176 offset:4096
	ds_read_b128 v[202:205], v176 offset:5120
	ds_read_b128 v[206:209], v176 offset:6144
	ds_read_b128 v[210:213], v176 offset:7168
	global_load_lds_dwordx4 v[214:215], off
	v_lshl_add_u64 v[214:215], s[34:35], 0, v[160:161]
	s_add_i32 m0, s9, 0xe000
	s_nop 0
	global_load_lds_dwordx4 v[214:215], off
	s_waitcnt vmcnt(8)
	s_waitcnt lgkmcnt(0)
	s_barrier
	v_mfma_f32_16x16x32_bf16 v[146:149], v[82:85], v[182:185], v[146:149]
	v_mfma_f32_16x16x32_bf16 v[138:141], v[94:97], v[182:185], v[138:141]
	v_mfma_f32_16x16x32_bf16 v[126:129], v[82:85], v[190:193], v[126:129]
	v_mfma_f32_16x16x32_bf16 v[118:121], v[94:97], v[190:193], v[118:121]
	v_mfma_f32_16x16x32_bf16 v[110:113], v[82:85], v[198:201], v[110:113]
	v_mfma_f32_16x16x32_bf16 v[98:101], v[94:97], v[198:201], v[98:101]
	v_mfma_f32_16x16x32_bf16 v[78:81], v[82:85], v[206:209], v[78:81]
	v_mfma_f32_16x16x32_bf16 v[70:73], v[94:97], v[206:209], v[70:73]
	v_mfma_f32_16x16x32_bf16 v[146:149], v[86:89], v[186:189], v[146:149]
	v_mfma_f32_16x16x32_bf16 v[138:141], v[102:105], v[186:189], v[138:141]
	v_mfma_f32_16x16x32_bf16 v[126:129], v[86:89], v[194:197], v[126:129]
	v_mfma_f32_16x16x32_bf16 v[118:121], v[102:105], v[194:197], v[118:121]
	v_mfma_f32_16x16x32_bf16 v[110:113], v[86:89], v[202:205], v[110:113]
	v_mfma_f32_16x16x32_bf16 v[98:101], v[102:105], v[202:205], v[98:101]
	v_mfma_f32_16x16x32_bf16 v[78:81], v[86:89], v[210:213], v[78:81]
	v_mfma_f32_16x16x32_bf16 v[70:73], v[102:105], v[210:213], v[70:73]
	v_mfma_f32_16x16x32_bf16 v[142:145], v[134:137], v[182:185], v[142:145]
	v_mfma_f32_16x16x32_bf16 v[130:133], v[166:169], v[182:185], v[130:133]
	v_mfma_f32_16x16x32_bf16 v[122:125], v[134:137], v[190:193], v[122:125]
	v_mfma_f32_16x16x32_bf16 v[114:117], v[166:169], v[190:193], v[114:117]
	v_mfma_f32_16x16x32_bf16 v[106:109], v[134:137], v[198:201], v[106:109]
	v_mfma_f32_16x16x32_bf16 v[90:93], v[166:169], v[198:201], v[90:93]
	v_mfma_f32_16x16x32_bf16 v[74:77], v[134:137], v[206:209], v[74:77]
	v_mfma_f32_16x16x32_bf16 v[66:69], v[166:169], v[206:209], v[66:69]
	v_mfma_f32_16x16x32_bf16 v[142:145], v[162:165], v[186:189], v[142:145]
	v_mfma_f32_16x16x32_bf16 v[130:133], v[178:181], v[186:189], v[130:133]
	v_mfma_f32_16x16x32_bf16 v[122:125], v[162:165], v[194:197], v[122:125]
	v_mfma_f32_16x16x32_bf16 v[114:117], v[178:181], v[194:197], v[114:117]
	v_mfma_f32_16x16x32_bf16 v[106:109], v[162:165], v[202:205], v[106:109]
	v_mfma_f32_16x16x32_bf16 v[90:93], v[178:181], v[202:205], v[90:93]
	v_mfma_f32_16x16x32_bf16 v[74:77], v[162:165], v[210:213], v[74:77]
	v_mfma_f32_16x16x32_bf16 v[66:69], v[178:181], v[210:213], v[66:69]
	s_barrier
	s_add_i32 s56, s56, s68
	v_lshl_add_u64 v[214:215], s[36:37], 0, v[154:155]
	s_mov_b32 m0, s56
	ds_read_b128 v[182:185], v176 offset:16384
	ds_read_b128 v[186:189], v176 offset:17408
	ds_read_b128 v[190:193], v176 offset:18432
	ds_read_b128 v[194:197], v176 offset:19456
	ds_read_b128 v[198:201], v176 offset:20480
	ds_read_b128 v[202:205], v176 offset:21504
	ds_read_b128 v[206:209], v176 offset:22528
	ds_read_b128 v[210:213], v176 offset:23552
	global_load_lds_dwordx4 v[214:215], off
	s_add_i32 m0, s56, 0x2000
	s_add_u32 s56, s36, 0x40000
	v_lshl_add_u64 v[216:217], s[36:37], 0, v[156:157]
	s_addc_u32 s57, s37, 0
	s_add_i32 s80, s80, s68
	global_load_lds_dwordx4 v[216:217], off
	v_lshl_add_u64 v[218:219], s[56:57], 0, v[154:155]
	s_mov_b32 m0, s80
	v_lshl_add_u64 v[220:221], s[38:39], 0, v[152:153]
	global_load_lds_dwordx4 v[218:219], off
	v_lshl_add_u64 v[218:219], s[56:57], 0, v[156:157]
	s_add_i32 m0, s80, 0x2000
	s_nop 0
	global_load_lds_dwordx4 v[218:219], off
	v_lshl_add_u64 v[218:219], s[38:39], 0, v[150:151]
	s_mov_b32 m0, s9
	s_nop 0
	global_load_lds_dwordx4 v[218:219], off
	s_mov_b32 m0, s69
	s_nop 0
	global_load_lds_dwordx4 v[220:221], off
	s_waitcnt vmcnt(8)
	s_waitcnt lgkmcnt(0)
	s_barrier
	v_mfma_f32_16x16x32_bf16 v[62:65], v[82:85], v[182:185], v[62:65]
	v_mfma_f32_16x16x32_bf16 v[54:57], v[94:97], v[182:185], v[54:57]
	v_mfma_f32_16x16x32_bf16 v[46:49], v[82:85], v[190:193], v[46:49]
	v_mfma_f32_16x16x32_bf16 v[38:41], v[94:97], v[190:193], v[38:41]
	v_mfma_f32_16x16x32_bf16 v[30:33], v[82:85], v[198:201], v[30:33]
	v_mfma_f32_16x16x32_bf16 v[22:25], v[94:97], v[198:201], v[22:25]
	v_mfma_f32_16x16x32_bf16 v[14:17], v[82:85], v[206:209], v[14:17]
	v_mfma_f32_16x16x32_bf16 v[6:9], v[94:97], v[206:209], v[6:9]
	v_mfma_f32_16x16x32_bf16 v[62:65], v[86:89], v[186:189], v[62:65]
	v_mfma_f32_16x16x32_bf16 v[54:57], v[102:105], v[186:189], v[54:57]
	v_mfma_f32_16x16x32_bf16 v[46:49], v[86:89], v[194:197], v[46:49]
	v_mfma_f32_16x16x32_bf16 v[38:41], v[102:105], v[194:197], v[38:41]
	v_mfma_f32_16x16x32_bf16 v[30:33], v[86:89], v[202:205], v[30:33]
	v_mfma_f32_16x16x32_bf16 v[22:25], v[102:105], v[202:205], v[22:25]
	v_mfma_f32_16x16x32_bf16 v[14:17], v[86:89], v[210:213], v[14:17]
	v_mfma_f32_16x16x32_bf16 v[6:9], v[102:105], v[210:213], v[6:9]
	v_mfma_f32_16x16x32_bf16 v[58:61], v[134:137], v[182:185], v[58:61]
	v_mfma_f32_16x16x32_bf16 v[50:53], v[166:169], v[182:185], v[50:53]
	v_mfma_f32_16x16x32_bf16 v[42:45], v[134:137], v[190:193], v[42:45]
	v_mfma_f32_16x16x32_bf16 v[34:37], v[166:169], v[190:193], v[34:37]
	v_mfma_f32_16x16x32_bf16 v[26:29], v[134:137], v[198:201], v[26:29]
	v_mfma_f32_16x16x32_bf16 v[18:21], v[166:169], v[198:201], v[18:21]
	v_mfma_f32_16x16x32_bf16 v[10:13], v[134:137], v[206:209], v[10:13]
	v_mfma_f32_16x16x32_bf16 v[2:5], v[166:169], v[206:209], v[2:5]
	v_mfma_f32_16x16x32_bf16 v[58:61], v[162:165], v[186:189], v[58:61]
	v_mfma_f32_16x16x32_bf16 v[50:53], v[178:181], v[186:189], v[50:53]
	v_mfma_f32_16x16x32_bf16 v[42:45], v[162:165], v[194:197], v[42:45]
	v_mfma_f32_16x16x32_bf16 v[34:37], v[178:181], v[194:197], v[34:37]
	v_mfma_f32_16x16x32_bf16 v[26:29], v[162:165], v[202:205], v[26:29]
	v_mfma_f32_16x16x32_bf16 v[18:21], v[178:181], v[202:205], v[18:21]
	v_mfma_f32_16x16x32_bf16 v[10:13], v[162:165], v[210:213], v[10:13]
	v_mfma_f32_16x16x32_bf16 v[2:5], v[178:181], v[210:213], v[2:5]
	s_barrier
	s_add_i32 s56, 0, 0x18000
	s_add_i32 s57, 0, 0x1c000
	v_add_u32_e32 v102, s56, v171
	v_add_u32_e32 v177, s57, v171
	ds_read_b128 v[82:85], v102
	ds_read_b128 v[86:89], v102 offset:1024
	ds_read_b128 v[94:97], v102 offset:2048
	ds_read_b128 v[102:105], v102 offset:3072
	ds_read_b128 v[134:137], v177
	ds_read_b128 v[162:165], v177 offset:1024
	ds_read_b128 v[166:169], v177 offset:2048
	ds_read_b128 v[178:181], v177 offset:3072
	s_add_u32 s38, s38, 0x40000
	s_addc_u32 s39, s39, 0
	s_mov_b32 m0, s70
	v_lshl_add_u64 v[232:233], s[38:39], 0, v[150:151]
	ds_read_b128 v[182:185], v176 offset:32768
	ds_read_b128 v[186:189], v176 offset:33792
	ds_read_b128 v[190:193], v176 offset:34816
	ds_read_b128 v[194:197], v176 offset:35840
	ds_read_b128 v[198:201], v176 offset:36864
	ds_read_b128 v[202:205], v176 offset:37888
	ds_read_b128 v[206:209], v176 offset:38912
	ds_read_b128 v[210:213], v176 offset:39936
	global_load_lds_dwordx4 v[232:233], off
	v_lshl_add_u64 v[232:233], s[38:39], 0, v[152:153]
	s_mov_b32 m0, s71
	s_nop 0
	global_load_lds_dwordx4 v[232:233], off
	s_waitcnt vmcnt(8)
	s_waitcnt lgkmcnt(0)
	s_barrier
	v_mfma_f32_16x16x32_bf16 v[146:149], v[82:85], v[182:185], v[146:149]
	v_mfma_f32_16x16x32_bf16 v[138:141], v[94:97], v[182:185], v[138:141]
	v_mfma_f32_16x16x32_bf16 v[126:129], v[82:85], v[190:193], v[126:129]
	v_mfma_f32_16x16x32_bf16 v[118:121], v[94:97], v[190:193], v[118:121]
	v_mfma_f32_16x16x32_bf16 v[110:113], v[82:85], v[198:201], v[110:113]
	v_mfma_f32_16x16x32_bf16 v[98:101], v[94:97], v[198:201], v[98:101]
	v_mfma_f32_16x16x32_bf16 v[78:81], v[82:85], v[206:209], v[78:81]
	v_mfma_f32_16x16x32_bf16 v[70:73], v[94:97], v[206:209], v[70:73]
	v_mfma_f32_16x16x32_bf16 v[146:149], v[86:89], v[186:189], v[146:149]
	v_mfma_f32_16x16x32_bf16 v[138:141], v[102:105], v[186:189], v[138:141]
	v_mfma_f32_16x16x32_bf16 v[126:129], v[86:89], v[194:197], v[126:129]
	v_mfma_f32_16x16x32_bf16 v[118:121], v[102:105], v[194:197], v[118:121]
	v_mfma_f32_16x16x32_bf16 v[110:113], v[86:89], v[202:205], v[110:113]
	v_mfma_f32_16x16x32_bf16 v[98:101], v[102:105], v[202:205], v[98:101]
	v_mfma_f32_16x16x32_bf16 v[78:81], v[86:89], v[210:213], v[78:81]
	v_mfma_f32_16x16x32_bf16 v[70:73], v[102:105], v[210:213], v[70:73]
	v_mfma_f32_16x16x32_bf16 v[142:145], v[134:137], v[182:185], v[142:145]
	v_mfma_f32_16x16x32_bf16 v[130:133], v[166:169], v[182:185], v[130:133]
	v_mfma_f32_16x16x32_bf16 v[122:125], v[134:137], v[190:193], v[122:125]
	v_mfma_f32_16x16x32_bf16 v[114:117], v[166:169], v[190:193], v[114:117]
	v_mfma_f32_16x16x32_bf16 v[106:109], v[134:137], v[198:201], v[106:109]
	v_mfma_f32_16x16x32_bf16 v[90:93], v[166:169], v[198:201], v[90:93]
	v_mfma_f32_16x16x32_bf16 v[74:77], v[134:137], v[206:209], v[74:77]
	v_mfma_f32_16x16x32_bf16 v[66:69], v[166:169], v[206:209], v[66:69]
	v_mfma_f32_16x16x32_bf16 v[142:145], v[162:165], v[186:189], v[142:145]
	v_mfma_f32_16x16x32_bf16 v[130:133], v[178:181], v[186:189], v[130:133]
	v_mfma_f32_16x16x32_bf16 v[122:125], v[162:165], v[194:197], v[122:125]
	v_mfma_f32_16x16x32_bf16 v[114:117], v[178:181], v[194:197], v[114:117]
	v_mfma_f32_16x16x32_bf16 v[106:109], v[162:165], v[202:205], v[106:109]
	v_mfma_f32_16x16x32_bf16 v[90:93], v[178:181], v[202:205], v[90:93]
	v_mfma_f32_16x16x32_bf16 v[74:77], v[162:165], v[210:213], v[74:77]
	v_mfma_f32_16x16x32_bf16 v[66:69], v[178:181], v[210:213], v[66:69]
	s_barrier
	s_add_i32 s38, s56, s68
	v_lshl_add_u64 v[214:215], v[214:215], 0, s[62:63]
	s_mov_b32 m0, s38
	ds_read_b128 v[182:185], v176 offset:49152
	ds_read_b128 v[186:189], v176 offset:50176
	ds_read_b128 v[190:193], v176 offset:51200
	ds_read_b128 v[194:197], v176 offset:52224
	ds_read_b128 v[198:201], v176 offset:53248
	ds_read_b128 v[202:205], v176 offset:54272
	ds_read_b128 v[206:209], v176 offset:55296
	ds_read_b128 v[210:213], v176 offset:56320
	global_load_lds_dwordx4 v[214:215], off
	s_add_i32 m0, s38, 0x2000
	s_add_u32 s36, s36, 0x40080
	v_lshl_add_u64 v[214:215], v[216:217], 0, s[62:63]
	s_addc_u32 s37, s37, 0
	s_add_i32 s38, s57, s68
	global_load_lds_dwordx4 v[214:215], off
	v_lshl_add_u64 v[214:215], s[36:37], 0, v[154:155]
	s_mov_b32 m0, s38
	s_nop 0
	global_load_lds_dwordx4 v[214:215], off
	v_lshl_add_u64 v[214:215], s[36:37], 0, v[156:157]
	s_add_i32 m0, s38, 0x2000
	s_nop 0
	global_load_lds_dwordx4 v[214:215], off
	v_lshl_add_u64 v[214:215], v[218:219], 0, s[62:63]
	s_mov_b32 m0, s73
	s_nop 0
	global_load_lds_dwordx4 v[214:215], off
	v_lshl_add_u64 v[214:215], v[220:221], 0, s[62:63]
	s_mov_b32 m0, s74
	s_nop 0
	global_load_lds_dwordx4 v[214:215], off
	s_waitcnt vmcnt(8)
	s_waitcnt lgkmcnt(0)
	s_barrier
	v_mfma_f32_16x16x32_bf16 v[62:65], v[82:85], v[182:185], v[62:65]
	v_mfma_f32_16x16x32_bf16 v[54:57], v[94:97], v[182:185], v[54:57]
	v_mfma_f32_16x16x32_bf16 v[46:49], v[82:85], v[190:193], v[46:49]
	v_mfma_f32_16x16x32_bf16 v[38:41], v[94:97], v[190:193], v[38:41]
	v_mfma_f32_16x16x32_bf16 v[30:33], v[82:85], v[198:201], v[30:33]
	v_mfma_f32_16x16x32_bf16 v[22:25], v[94:97], v[198:201], v[22:25]
	v_mfma_f32_16x16x32_bf16 v[14:17], v[82:85], v[206:209], v[14:17]
	v_mfma_f32_16x16x32_bf16 v[6:9], v[94:97], v[206:209], v[6:9]
	v_mfma_f32_16x16x32_bf16 v[62:65], v[86:89], v[186:189], v[62:65]
	v_mfma_f32_16x16x32_bf16 v[54:57], v[102:105], v[186:189], v[54:57]
	v_mfma_f32_16x16x32_bf16 v[46:49], v[86:89], v[194:197], v[46:49]
	v_mfma_f32_16x16x32_bf16 v[38:41], v[102:105], v[194:197], v[38:41]
	v_mfma_f32_16x16x32_bf16 v[30:33], v[86:89], v[202:205], v[30:33]
	v_mfma_f32_16x16x32_bf16 v[22:25], v[102:105], v[202:205], v[22:25]
	v_mfma_f32_16x16x32_bf16 v[14:17], v[86:89], v[210:213], v[14:17]
	v_mfma_f32_16x16x32_bf16 v[6:9], v[102:105], v[210:213], v[6:9]
	v_mfma_f32_16x16x32_bf16 v[58:61], v[134:137], v[182:185], v[58:61]
	v_mfma_f32_16x16x32_bf16 v[50:53], v[166:169], v[182:185], v[50:53]
	v_mfma_f32_16x16x32_bf16 v[42:45], v[134:137], v[190:193], v[42:45]
	v_mfma_f32_16x16x32_bf16 v[34:37], v[166:169], v[190:193], v[34:37]
	v_mfma_f32_16x16x32_bf16 v[26:29], v[134:137], v[198:201], v[26:29]
	v_mfma_f32_16x16x32_bf16 v[18:21], v[166:169], v[198:201], v[18:21]
	v_mfma_f32_16x16x32_bf16 v[10:13], v[134:137], v[206:209], v[10:13]
	v_mfma_f32_16x16x32_bf16 v[2:5], v[166:169], v[206:209], v[2:5]
	v_mfma_f32_16x16x32_bf16 v[58:61], v[162:165], v[186:189], v[58:61]
	v_mfma_f32_16x16x32_bf16 v[50:53], v[178:181], v[186:189], v[50:53]
	v_mfma_f32_16x16x32_bf16 v[42:45], v[162:165], v[194:197], v[42:45]
	v_mfma_f32_16x16x32_bf16 v[34:37], v[178:181], v[194:197], v[34:37]
	v_mfma_f32_16x16x32_bf16 v[26:29], v[162:165], v[202:205], v[26:29]
	v_mfma_f32_16x16x32_bf16 v[18:21], v[178:181], v[202:205], v[18:21]
	v_mfma_f32_16x16x32_bf16 v[10:13], v[162:165], v[210:213], v[10:13]
	v_mfma_f32_16x16x32_bf16 v[2:5], v[178:181], v[210:213], v[2:5]
	s_barrier
	s_add_i32 s79, s79, 2
	s_add_u32 s34, s34, 0x100
	s_addc_u32 s35, s35, 0
	s_add_u32 s77, s77, 0x100
	s_addc_u32 s78, s78, 0
	s_cmp_gt_u32 s79, 13
	s_cbranch_scc0 .LBB0_341
	s_and_b64 vcc, exec, s[18:19]
	s_cbranch_vccz .LBB0_344
	s_barrier

.LBB0_445:
	s_add_u32 s22, s20, 0xfffc0080
	s_addc_u32 s23, s21, -1
	s_add_i32 s56, 0, 0x10000
	s_cmp_eq_u32 s70, 12
	s_cselect_b32 s25, s13, s23
	s_cselect_b32 s24, s66, s22
	v_add_u32_e32 v152, s56, v145
	s_cselect_b32 s23, s11, s69
	s_cselect_b32 s22, s67, s68
	s_add_i32 s71, 0, 0x14000
	ds_read_b128 v[140:143], v152
	ds_read_b128 v[148:151], v152 offset:1024
	ds_read_b128 v[156:159], v152 offset:2048
	ds_read_b128 v[160:163], v152 offset:3072
	v_add_u32_e32 v152, s71, v145
	ds_read_b128 v[164:167], v152
	ds_read_b128 v[168:171], v152 offset:1024
	ds_read_b128 v[172:175], v152 offset:2048
	ds_read_b128 v[176:179], v152 offset:3072
	v_lshl_add_u64 v[152:153], s[20:21], 0, v[136:137]
	s_add_i32 m0, s19, 0xc000
	ds_read_b128 v[180:183], v147
	ds_read_b128 v[184:187], v147 offset:1024
	ds_read_b128 v[188:191], v147 offset:2048
	ds_read_b128 v[192:195], v147 offset:3072
	ds_read_b128 v[196:199], v147 offset:4096
	ds_read_b128 v[200:203], v147 offset:5120
	ds_read_b128 v[204:207], v147 offset:6144
	ds_read_b128 v[208:211], v147 offset:7168
	global_load_lds_dwordx4 v[152:153], off
	v_lshl_add_u64 v[152:153], s[20:21], 0, v[138:139]
	s_add_i32 m0, s19, 0xe000
	s_nop 0
	global_load_lds_dwordx4 v[152:153], off
	s_waitcnt vmcnt(8)
	s_waitcnt lgkmcnt(0)
	s_barrier
	v_mfma_f32_16x16x32_bf16 v[126:129], v[140:143], v[180:183], v[126:129]
	v_mfma_f32_16x16x32_bf16 v[122:125], v[156:159], v[180:183], v[122:125]
	v_mfma_f32_16x16x32_bf16 v[110:113], v[140:143], v[188:191], v[110:113]
	v_mfma_f32_16x16x32_bf16 v[106:109], v[156:159], v[188:191], v[106:109]
	v_mfma_f32_16x16x32_bf16 v[94:97], v[140:143], v[196:199], v[94:97]
	v_mfma_f32_16x16x32_bf16 v[90:93], v[156:159], v[196:199], v[90:93]
	v_mfma_f32_16x16x32_bf16 v[78:81], v[140:143], v[204:207], v[78:81]
	v_mfma_f32_16x16x32_bf16 v[74:77], v[156:159], v[204:207], v[74:77]
	v_mfma_f32_16x16x32_bf16 v[126:129], v[148:151], v[184:187], v[126:129]
	v_mfma_f32_16x16x32_bf16 v[122:125], v[160:163], v[184:187], v[122:125]
	v_mfma_f32_16x16x32_bf16 v[110:113], v[148:151], v[192:195], v[110:113]
	v_mfma_f32_16x16x32_bf16 v[106:109], v[160:163], v[192:195], v[106:109]
	v_mfma_f32_16x16x32_bf16 v[94:97], v[148:151], v[200:203], v[94:97]
	v_mfma_f32_16x16x32_bf16 v[90:93], v[160:163], v[200:203], v[90:93]
	v_mfma_f32_16x16x32_bf16 v[78:81], v[148:151], v[208:211], v[78:81]
	v_mfma_f32_16x16x32_bf16 v[74:77], v[160:163], v[208:211], v[74:77]
	v_mfma_f32_16x16x32_bf16 v[118:121], v[164:167], v[180:183], v[118:121]
	v_mfma_f32_16x16x32_bf16 v[114:117], v[172:175], v[180:183], v[114:117]
	v_mfma_f32_16x16x32_bf16 v[102:105], v[164:167], v[188:191], v[102:105]
	v_mfma_f32_16x16x32_bf16 v[98:101], v[172:175], v[188:191], v[98:101]
	v_mfma_f32_16x16x32_bf16 v[86:89], v[164:167], v[196:199], v[86:89]
	v_mfma_f32_16x16x32_bf16 v[82:85], v[172:175], v[196:199], v[82:85]
	v_mfma_f32_16x16x32_bf16 v[70:73], v[164:167], v[204:207], v[70:73]
	v_mfma_f32_16x16x32_bf16 v[66:69], v[172:175], v[204:207], v[66:69]
	v_mfma_f32_16x16x32_bf16 v[118:121], v[168:171], v[184:187], v[118:121]
	v_mfma_f32_16x16x32_bf16 v[114:117], v[176:179], v[184:187], v[114:117]
	v_mfma_f32_16x16x32_bf16 v[102:105], v[168:171], v[192:195], v[102:105]
	v_mfma_f32_16x16x32_bf16 v[98:101], v[176:179], v[192:195], v[98:101]
	v_mfma_f32_16x16x32_bf16 v[86:89], v[168:171], v[200:203], v[86:89]
	v_mfma_f32_16x16x32_bf16 v[82:85], v[176:179], v[200:203], v[82:85]
	v_mfma_f32_16x16x32_bf16 v[70:73], v[168:171], v[208:211], v[70:73]
	v_mfma_f32_16x16x32_bf16 v[66:69], v[176:179], v[208:211], v[66:69]
	s_barrier
	s_add_i32 s56, s56, s35
	v_lshl_add_u64 v[152:153], s[22:23], 0, v[154:155]
	s_mov_b32 m0, s56
	ds_read_b128 v[180:183], v147 offset:16384
	ds_read_b128 v[184:187], v147 offset:17408
	ds_read_b128 v[188:191], v147 offset:18432
	ds_read_b128 v[192:195], v147 offset:19456
	ds_read_b128 v[196:199], v147 offset:20480
	ds_read_b128 v[200:203], v147 offset:21504
	ds_read_b128 v[204:207], v147 offset:22528
	ds_read_b128 v[208:211], v147 offset:23552
	global_load_lds_dwordx4 v[152:153], off
	s_add_i32 m0, s56, 0x2000
	s_add_u32 s56, s22, 0x40000
	v_lshl_add_u64 v[212:213], s[22:23], 0, v[134:135]
	s_addc_u32 s57, s23, 0
	s_add_i32 s71, s71, s35
	global_load_lds_dwordx4 v[212:213], off
	v_lshl_add_u64 v[214:215], s[56:57], 0, v[154:155]
	s_mov_b32 m0, s71
	v_lshl_add_u64 v[216:217], s[24:25], 0, v[132:133]
	global_load_lds_dwordx4 v[214:215], off
	v_lshl_add_u64 v[214:215], s[56:57], 0, v[134:135]
	s_add_i32 m0, s71, 0x2000
	s_nop 0
	global_load_lds_dwordx4 v[214:215], off
	v_lshl_add_u64 v[214:215], s[24:25], 0, v[130:131]
	s_mov_b32 m0, s19
	s_nop 0
	global_load_lds_dwordx4 v[214:215], off
	s_mov_b32 m0, s36
	s_nop 0
	global_load_lds_dwordx4 v[216:217], off
	s_waitcnt vmcnt(8)
	s_waitcnt lgkmcnt(0)
	s_barrier
	v_mfma_f32_16x16x32_bf16 v[62:65], v[140:143], v[180:183], v[62:65]
	v_mfma_f32_16x16x32_bf16 v[58:61], v[156:159], v[180:183], v[58:61]
	v_mfma_f32_16x16x32_bf16 v[46:49], v[140:143], v[188:191], v[46:49]
	v_mfma_f32_16x16x32_bf16 v[42:45], v[156:159], v[188:191], v[42:45]
	v_mfma_f32_16x16x32_bf16 v[30:33], v[140:143], v[196:199], v[30:33]
	v_mfma_f32_16x16x32_bf16 v[26:29], v[156:159], v[196:199], v[26:29]
	v_mfma_f32_16x16x32_bf16 v[14:17], v[140:143], v[204:207], v[14:17]
	v_mfma_f32_16x16x32_bf16 v[10:13], v[156:159], v[204:207], v[10:13]
	v_mfma_f32_16x16x32_bf16 v[62:65], v[148:151], v[184:187], v[62:65]
	v_mfma_f32_16x16x32_bf16 v[58:61], v[160:163], v[184:187], v[58:61]
	v_mfma_f32_16x16x32_bf16 v[46:49], v[148:151], v[192:195], v[46:49]
	v_mfma_f32_16x16x32_bf16 v[42:45], v[160:163], v[192:195], v[42:45]
	v_mfma_f32_16x16x32_bf16 v[30:33], v[148:151], v[200:203], v[30:33]
	v_mfma_f32_16x16x32_bf16 v[26:29], v[160:163], v[200:203], v[26:29]
	v_mfma_f32_16x16x32_bf16 v[14:17], v[148:151], v[208:211], v[14:17]
	v_mfma_f32_16x16x32_bf16 v[10:13], v[160:163], v[208:211], v[10:13]
	v_mfma_f32_16x16x32_bf16 v[54:57], v[164:167], v[180:183], v[54:57]
	v_mfma_f32_16x16x32_bf16 v[50:53], v[172:175], v[180:183], v[50:53]
	v_mfma_f32_16x16x32_bf16 v[38:41], v[164:167], v[188:191], v[38:41]
	v_mfma_f32_16x16x32_bf16 v[34:37], v[172:175], v[188:191], v[34:37]
	v_mfma_f32_16x16x32_bf16 v[22:25], v[164:167], v[196:199], v[22:25]
	v_mfma_f32_16x16x32_bf16 v[18:21], v[172:175], v[196:199], v[18:21]
	v_mfma_f32_16x16x32_bf16 v[6:9], v[164:167], v[204:207], v[6:9]
	v_mfma_f32_16x16x32_bf16 v[2:5], v[172:175], v[204:207], v[2:5]
	v_mfma_f32_16x16x32_bf16 v[54:57], v[168:171], v[184:187], v[54:57]
	v_mfma_f32_16x16x32_bf16 v[50:53], v[176:179], v[184:187], v[50:53]
	v_mfma_f32_16x16x32_bf16 v[38:41], v[168:171], v[192:195], v[38:41]
	v_mfma_f32_16x16x32_bf16 v[34:37], v[176:179], v[192:195], v[34:37]
	v_mfma_f32_16x16x32_bf16 v[22:25], v[168:171], v[200:203], v[22:25]
	v_mfma_f32_16x16x32_bf16 v[18:21], v[176:179], v[200:203], v[18:21]
	v_mfma_f32_16x16x32_bf16 v[6:9], v[168:171], v[208:211], v[6:9]
	v_mfma_f32_16x16x32_bf16 v[2:5], v[176:179], v[208:211], v[2:5]
	s_barrier
	s_add_i32 s56, 0, 0x18000
	s_add_i32 s57, 0, 0x1c000
	v_add_u32_e32 v160, s56, v145
	v_add_u32_e32 v176, s57, v145
	ds_read_b128 v[140:143], v160
	ds_read_b128 v[148:151], v160 offset:1024
	ds_read_b128 v[156:159], v160 offset:2048
	ds_read_b128 v[160:163], v160 offset:3072
	ds_read_b128 v[164:167], v176
	ds_read_b128 v[168:171], v176 offset:1024
	ds_read_b128 v[172:175], v176 offset:2048
	ds_read_b128 v[176:179], v176 offset:3072
	s_add_u32 s24, s24, 0x40000
	s_addc_u32 s25, s25, 0
	s_mov_b32 m0, s37
	v_lshl_add_u64 v[218:219], s[24:25], 0, v[130:131]
	ds_read_b128 v[180:183], v147 offset:32768
	ds_read_b128 v[184:187], v147 offset:33792
	ds_read_b128 v[188:191], v147 offset:34816
	ds_read_b128 v[192:195], v147 offset:35840
	ds_read_b128 v[196:199], v147 offset:36864
	ds_read_b128 v[200:203], v147 offset:37888
	ds_read_b128 v[204:207], v147 offset:38912
	ds_read_b128 v[208:211], v147 offset:39936
	global_load_lds_dwordx4 v[218:219], off
	v_lshl_add_u64 v[218:219], s[24:25], 0, v[132:133]
	s_mov_b32 m0, s38
	s_nop 0
	global_load_lds_dwordx4 v[218:219], off
	s_waitcnt vmcnt(8)
	s_waitcnt lgkmcnt(0)
	s_barrier
	v_mfma_f32_16x16x32_bf16 v[126:129], v[140:143], v[180:183], v[126:129]
	v_mfma_f32_16x16x32_bf16 v[122:125], v[156:159], v[180:183], v[122:125]
	v_mfma_f32_16x16x32_bf16 v[110:113], v[140:143], v[188:191], v[110:113]
	v_mfma_f32_16x16x32_bf16 v[106:109], v[156:159], v[188:191], v[106:109]
	v_mfma_f32_16x16x32_bf16 v[94:97], v[140:143], v[196:199], v[94:97]
	v_mfma_f32_16x16x32_bf16 v[90:93], v[156:159], v[196:199], v[90:93]
	v_mfma_f32_16x16x32_bf16 v[78:81], v[140:143], v[204:207], v[78:81]
	v_mfma_f32_16x16x32_bf16 v[74:77], v[156:159], v[204:207], v[74:77]
	v_mfma_f32_16x16x32_bf16 v[126:129], v[148:151], v[184:187], v[126:129]
	v_mfma_f32_16x16x32_bf16 v[122:125], v[160:163], v[184:187], v[122:125]
	v_mfma_f32_16x16x32_bf16 v[110:113], v[148:151], v[192:195], v[110:113]
	v_mfma_f32_16x16x32_bf16 v[106:109], v[160:163], v[192:195], v[106:109]
	v_mfma_f32_16x16x32_bf16 v[94:97], v[148:151], v[200:203], v[94:97]
	v_mfma_f32_16x16x32_bf16 v[90:93], v[160:163], v[200:203], v[90:93]
	v_mfma_f32_16x16x32_bf16 v[78:81], v[148:151], v[208:211], v[78:81]
	v_mfma_f32_16x16x32_bf16 v[74:77], v[160:163], v[208:211], v[74:77]
	v_mfma_f32_16x16x32_bf16 v[118:121], v[164:167], v[180:183], v[118:121]
	v_mfma_f32_16x16x32_bf16 v[114:117], v[172:175], v[180:183], v[114:117]
	v_mfma_f32_16x16x32_bf16 v[102:105], v[164:167], v[188:191], v[102:105]
	v_mfma_f32_16x16x32_bf16 v[98:101], v[172:175], v[188:191], v[98:101]
	v_mfma_f32_16x16x32_bf16 v[86:89], v[164:167], v[196:199], v[86:89]
	v_mfma_f32_16x16x32_bf16 v[82:85], v[172:175], v[196:199], v[82:85]
	v_mfma_f32_16x16x32_bf16 v[70:73], v[164:167], v[204:207], v[70:73]
	v_mfma_f32_16x16x32_bf16 v[66:69], v[172:175], v[204:207], v[66:69]
	v_mfma_f32_16x16x32_bf16 v[118:121], v[168:171], v[184:187], v[118:121]
	v_mfma_f32_16x16x32_bf16 v[114:117], v[176:179], v[184:187], v[114:117]
	v_mfma_f32_16x16x32_bf16 v[102:105], v[168:171], v[192:195], v[102:105]
	v_mfma_f32_16x16x32_bf16 v[98:101], v[176:179], v[192:195], v[98:101]
	v_mfma_f32_16x16x32_bf16 v[86:89], v[168:171], v[200:203], v[86:89]
	v_mfma_f32_16x16x32_bf16 v[82:85], v[176:179], v[200:203], v[82:85]
	v_mfma_f32_16x16x32_bf16 v[70:73], v[168:171], v[208:211], v[70:73]
	v_mfma_f32_16x16x32_bf16 v[66:69], v[176:179], v[208:211], v[66:69]
	s_barrier
	s_add_i32 s24, s56, s35
	v_lshl_add_u64 v[152:153], v[152:153], 0, s[62:63]
	s_mov_b32 m0, s24
	ds_read_b128 v[180:183], v147 offset:49152
	ds_read_b128 v[184:187], v147 offset:50176
	ds_read_b128 v[188:191], v147 offset:51200
	ds_read_b128 v[192:195], v147 offset:52224
	ds_read_b128 v[196:199], v147 offset:53248
	ds_read_b128 v[200:203], v147 offset:54272
	ds_read_b128 v[204:207], v147 offset:55296
	ds_read_b128 v[208:211], v147 offset:56320
	global_load_lds_dwordx4 v[152:153], off
	s_add_i32 m0, s24, 0x2000
	s_add_u32 s22, s22, 0x40080
	v_lshl_add_u64 v[152:153], v[212:213], 0, s[62:63]
	s_addc_u32 s23, s23, 0
	s_add_i32 s24, s57, s35
	global_load_lds_dwordx4 v[152:153], off
	v_lshl_add_u64 v[152:153], s[22:23], 0, v[154:155]
	s_mov_b32 m0, s24
	s_nop 0
	global_load_lds_dwordx4 v[152:153], off
	v_lshl_add_u64 v[152:153], s[22:23], 0, v[134:135]
	s_add_i32 m0, s24, 0x2000
	s_nop 0
	global_load_lds_dwordx4 v[152:153], off
	v_lshl_add_u64 v[152:153], v[214:215], 0, s[62:63]
	s_mov_b32 m0, s39
	s_nop 0
	global_load_lds_dwordx4 v[152:153], off
	v_lshl_add_u64 v[152:153], v[216:217], 0, s[62:63]
	s_mov_b32 m0, s40
	s_nop 0
	global_load_lds_dwordx4 v[152:153], off
	s_waitcnt vmcnt(8)
	s_waitcnt lgkmcnt(0)
	s_barrier
	v_mfma_f32_16x16x32_bf16 v[62:65], v[140:143], v[180:183], v[62:65]
	v_mfma_f32_16x16x32_bf16 v[58:61], v[156:159], v[180:183], v[58:61]
	v_mfma_f32_16x16x32_bf16 v[46:49], v[140:143], v[188:191], v[46:49]
	v_mfma_f32_16x16x32_bf16 v[42:45], v[156:159], v[188:191], v[42:45]
	v_mfma_f32_16x16x32_bf16 v[30:33], v[140:143], v[196:199], v[30:33]
	v_mfma_f32_16x16x32_bf16 v[26:29], v[156:159], v[196:199], v[26:29]
	v_mfma_f32_16x16x32_bf16 v[14:17], v[140:143], v[204:207], v[14:17]
	v_mfma_f32_16x16x32_bf16 v[10:13], v[156:159], v[204:207], v[10:13]
	v_mfma_f32_16x16x32_bf16 v[62:65], v[148:151], v[184:187], v[62:65]
	v_mfma_f32_16x16x32_bf16 v[58:61], v[160:163], v[184:187], v[58:61]
	v_mfma_f32_16x16x32_bf16 v[46:49], v[148:151], v[192:195], v[46:49]
	v_mfma_f32_16x16x32_bf16 v[42:45], v[160:163], v[192:195], v[42:45]
	v_mfma_f32_16x16x32_bf16 v[30:33], v[148:151], v[200:203], v[30:33]
	v_mfma_f32_16x16x32_bf16 v[26:29], v[160:163], v[200:203], v[26:29]
	v_mfma_f32_16x16x32_bf16 v[14:17], v[148:151], v[208:211], v[14:17]
	v_mfma_f32_16x16x32_bf16 v[10:13], v[160:163], v[208:211], v[10:13]
	v_mfma_f32_16x16x32_bf16 v[54:57], v[164:167], v[180:183], v[54:57]
	v_mfma_f32_16x16x32_bf16 v[50:53], v[172:175], v[180:183], v[50:53]
	v_mfma_f32_16x16x32_bf16 v[38:41], v[164:167], v[188:191], v[38:41]
	v_mfma_f32_16x16x32_bf16 v[34:37], v[172:175], v[188:191], v[34:37]
	v_mfma_f32_16x16x32_bf16 v[22:25], v[164:167], v[196:199], v[22:25]
	v_mfma_f32_16x16x32_bf16 v[18:21], v[172:175], v[196:199], v[18:21]
	v_mfma_f32_16x16x32_bf16 v[6:9], v[164:167], v[204:207], v[6:9]
	v_mfma_f32_16x16x32_bf16 v[2:5], v[172:175], v[204:207], v[2:5]
	v_mfma_f32_16x16x32_bf16 v[54:57], v[168:171], v[184:187], v[54:57]
	v_mfma_f32_16x16x32_bf16 v[50:53], v[176:179], v[184:187], v[50:53]
	v_mfma_f32_16x16x32_bf16 v[38:41], v[168:171], v[192:195], v[38:41]
	v_mfma_f32_16x16x32_bf16 v[34:37], v[176:179], v[192:195], v[34:37]
	v_mfma_f32_16x16x32_bf16 v[22:25], v[168:171], v[200:203], v[22:25]
	v_mfma_f32_16x16x32_bf16 v[18:21], v[176:179], v[200:203], v[18:21]
	v_mfma_f32_16x16x32_bf16 v[6:9], v[168:171], v[208:211], v[6:9]
	v_mfma_f32_16x16x32_bf16 v[2:5], v[176:179], v[208:211], v[2:5]
	s_barrier
	s_add_i32 s70, s70, 2
	s_add_u32 s20, s20, 0x100
	s_addc_u32 s21, s21, 0
	s_add_u32 s68, s68, 0x100
	s_addc_u32 s69, s69, 0
	s_cmp_gt_u32 s70, 13
	s_cbranch_scc0 .LBB0_445
	s_and_b64 vcc, exec, s[8:9]
	s_cbranch_vccz .LBB0_448
	s_barrier

.LBB0_534:
	s_add_u32 s24, s22, 0xfff00080
	s_addc_u32 s25, s23, -1
	s_add_i32 s56, 0, 0x10000
	s_cmp_eq_u32 s69, 60
	s_cselect_b32 s27, s13, s25
	s_cselect_b32 s26, s19, s24
	v_add_u32_e32 v152, s56, v159
	s_cselect_b32 s25, s11, s68
	s_cselect_b32 s24, s21, s40
	s_add_i32 s70, 0, 0x14000
	ds_read_b128 v[130:133], v152
	ds_read_b128 v[134:137], v152 offset:1024
	ds_read_b128 v[148:151], v152 offset:2048
	ds_read_b128 v[162:165], v152 offset:3072
	v_add_u32_e32 v152, s70, v159
	ds_read_b128 v[166:169], v152
	ds_read_b128 v[170:173], v152 offset:1024
	ds_read_b128 v[174:177], v152 offset:2048
	ds_read_b128 v[178:181], v152 offset:3072
	v_lshl_add_u64 v[152:153], s[22:23], 0, v[144:145]
	s_add_i32 m0, s38, 0xc000
	ds_read_b128 v[182:185], v161
	ds_read_b128 v[186:189], v161 offset:1024
	ds_read_b128 v[190:193], v161 offset:2048
	ds_read_b128 v[194:197], v161 offset:3072
	ds_read_b128 v[198:201], v161 offset:4096
	ds_read_b128 v[202:205], v161 offset:5120
	ds_read_b128 v[206:209], v161 offset:6144
	ds_read_b128 v[210:213], v161 offset:7168
	global_load_lds_dwordx4 v[152:153], off
	v_lshl_add_u64 v[152:153], s[22:23], 0, v[146:147]
	s_add_i32 m0, s38, 0xe000
	s_nop 0
	global_load_lds_dwordx4 v[152:153], off
	s_waitcnt vmcnt(8)
	s_waitcnt lgkmcnt(0)
	s_barrier
	v_mfma_f32_16x16x32_bf16 v[126:129], v[130:133], v[182:185], v[126:129]
	v_mfma_f32_16x16x32_bf16 v[122:125], v[148:151], v[182:185], v[122:125]
	v_mfma_f32_16x16x32_bf16 v[110:113], v[130:133], v[190:193], v[110:113]
	v_mfma_f32_16x16x32_bf16 v[106:109], v[148:151], v[190:193], v[106:109]
	v_mfma_f32_16x16x32_bf16 v[94:97], v[130:133], v[198:201], v[94:97]
	v_mfma_f32_16x16x32_bf16 v[90:93], v[148:151], v[198:201], v[90:93]
	v_mfma_f32_16x16x32_bf16 v[78:81], v[130:133], v[206:209], v[78:81]
	v_mfma_f32_16x16x32_bf16 v[74:77], v[148:151], v[206:209], v[74:77]
	v_mfma_f32_16x16x32_bf16 v[126:129], v[134:137], v[186:189], v[126:129]
	v_mfma_f32_16x16x32_bf16 v[122:125], v[162:165], v[186:189], v[122:125]
	v_mfma_f32_16x16x32_bf16 v[110:113], v[134:137], v[194:197], v[110:113]
	v_mfma_f32_16x16x32_bf16 v[106:109], v[162:165], v[194:197], v[106:109]
	v_mfma_f32_16x16x32_bf16 v[94:97], v[134:137], v[202:205], v[94:97]
	v_mfma_f32_16x16x32_bf16 v[90:93], v[162:165], v[202:205], v[90:93]
	v_mfma_f32_16x16x32_bf16 v[78:81], v[134:137], v[210:213], v[78:81]
	v_mfma_f32_16x16x32_bf16 v[74:77], v[162:165], v[210:213], v[74:77]
	v_mfma_f32_16x16x32_bf16 v[118:121], v[166:169], v[182:185], v[118:121]
	v_mfma_f32_16x16x32_bf16 v[114:117], v[174:177], v[182:185], v[114:117]
	v_mfma_f32_16x16x32_bf16 v[102:105], v[166:169], v[190:193], v[102:105]
	v_mfma_f32_16x16x32_bf16 v[98:101], v[174:177], v[190:193], v[98:101]
	v_mfma_f32_16x16x32_bf16 v[86:89], v[166:169], v[198:201], v[86:89]
	v_mfma_f32_16x16x32_bf16 v[82:85], v[174:177], v[198:201], v[82:85]
	v_mfma_f32_16x16x32_bf16 v[70:73], v[166:169], v[206:209], v[70:73]
	v_mfma_f32_16x16x32_bf16 v[66:69], v[174:177], v[206:209], v[66:69]
	v_mfma_f32_16x16x32_bf16 v[118:121], v[170:173], v[186:189], v[118:121]
	v_mfma_f32_16x16x32_bf16 v[114:117], v[178:181], v[186:189], v[114:117]
	v_mfma_f32_16x16x32_bf16 v[102:105], v[170:173], v[194:197], v[102:105]
	v_mfma_f32_16x16x32_bf16 v[98:101], v[178:181], v[194:197], v[98:101]
	v_mfma_f32_16x16x32_bf16 v[86:89], v[170:173], v[202:205], v[86:89]
	v_mfma_f32_16x16x32_bf16 v[82:85], v[178:181], v[202:205], v[82:85]
	v_mfma_f32_16x16x32_bf16 v[70:73], v[170:173], v[210:213], v[70:73]
	v_mfma_f32_16x16x32_bf16 v[66:69], v[178:181], v[210:213], v[66:69]
	s_barrier
	s_add_i32 s56, s56, s37
	v_lshl_add_u64 v[152:153], s[24:25], 0, v[154:155]
	s_mov_b32 m0, s56
	ds_read_b128 v[182:185], v161 offset:16384
	ds_read_b128 v[186:189], v161 offset:17408
	ds_read_b128 v[190:193], v161 offset:18432
	ds_read_b128 v[194:197], v161 offset:19456
	ds_read_b128 v[198:201], v161 offset:20480
	ds_read_b128 v[202:205], v161 offset:21504
	ds_read_b128 v[206:209], v161 offset:22528
	ds_read_b128 v[210:213], v161 offset:23552
	global_load_lds_dwordx4 v[152:153], off
	s_add_i32 m0, s56, 0x2000
	s_add_u32 s56, s24, 0x100000
	v_lshl_add_u64 v[156:157], s[24:25], 0, v[142:143]
	s_addc_u32 s57, s25, 0
	s_add_i32 s70, s70, s37
	global_load_lds_dwordx4 v[156:157], off
	v_lshl_add_u64 v[214:215], s[56:57], 0, v[154:155]
	s_mov_b32 m0, s70
	v_lshl_add_u64 v[216:217], s[26:27], 0, v[140:141]
	global_load_lds_dwordx4 v[214:215], off
	v_lshl_add_u64 v[214:215], s[56:57], 0, v[142:143]
	s_add_i32 m0, s70, 0x2000
	s_nop 0
	global_load_lds_dwordx4 v[214:215], off
	v_lshl_add_u64 v[214:215], s[26:27], 0, v[138:139]
	s_mov_b32 m0, s38
	s_nop 0
	global_load_lds_dwordx4 v[214:215], off
	s_mov_b32 m0, s39
	s_nop 0
	global_load_lds_dwordx4 v[216:217], off
	s_waitcnt vmcnt(8)
	s_waitcnt lgkmcnt(0)
	s_barrier
	v_mfma_f32_16x16x32_bf16 v[62:65], v[130:133], v[182:185], v[62:65]
	v_mfma_f32_16x16x32_bf16 v[58:61], v[148:151], v[182:185], v[58:61]
	v_mfma_f32_16x16x32_bf16 v[46:49], v[130:133], v[190:193], v[46:49]
	v_mfma_f32_16x16x32_bf16 v[42:45], v[148:151], v[190:193], v[42:45]
	v_mfma_f32_16x16x32_bf16 v[30:33], v[130:133], v[198:201], v[30:33]
	v_mfma_f32_16x16x32_bf16 v[26:29], v[148:151], v[198:201], v[26:29]
	v_mfma_f32_16x16x32_bf16 v[14:17], v[130:133], v[206:209], v[14:17]
	v_mfma_f32_16x16x32_bf16 v[10:13], v[148:151], v[206:209], v[10:13]
	v_mfma_f32_16x16x32_bf16 v[62:65], v[134:137], v[186:189], v[62:65]
	v_mfma_f32_16x16x32_bf16 v[58:61], v[162:165], v[186:189], v[58:61]
	v_mfma_f32_16x16x32_bf16 v[46:49], v[134:137], v[194:197], v[46:49]
	v_mfma_f32_16x16x32_bf16 v[42:45], v[162:165], v[194:197], v[42:45]
	v_mfma_f32_16x16x32_bf16 v[30:33], v[134:137], v[202:205], v[30:33]
	v_mfma_f32_16x16x32_bf16 v[26:29], v[162:165], v[202:205], v[26:29]
	v_mfma_f32_16x16x32_bf16 v[14:17], v[134:137], v[210:213], v[14:17]
	v_mfma_f32_16x16x32_bf16 v[10:13], v[162:165], v[210:213], v[10:13]
	v_mfma_f32_16x16x32_bf16 v[54:57], v[166:169], v[182:185], v[54:57]
	v_mfma_f32_16x16x32_bf16 v[50:53], v[174:177], v[182:185], v[50:53]
	v_mfma_f32_16x16x32_bf16 v[38:41], v[166:169], v[190:193], v[38:41]
	v_mfma_f32_16x16x32_bf16 v[34:37], v[174:177], v[190:193], v[34:37]
	v_mfma_f32_16x16x32_bf16 v[22:25], v[166:169], v[198:201], v[22:25]
	v_mfma_f32_16x16x32_bf16 v[18:21], v[174:177], v[198:201], v[18:21]
	v_mfma_f32_16x16x32_bf16 v[6:9], v[166:169], v[206:209], v[6:9]
	v_mfma_f32_16x16x32_bf16 v[2:5], v[174:177], v[206:209], v[2:5]
	v_mfma_f32_16x16x32_bf16 v[54:57], v[170:173], v[186:189], v[54:57]
	v_mfma_f32_16x16x32_bf16 v[50:53], v[178:181], v[186:189], v[50:53]
	v_mfma_f32_16x16x32_bf16 v[38:41], v[170:173], v[194:197], v[38:41]
	v_mfma_f32_16x16x32_bf16 v[34:37], v[178:181], v[194:197], v[34:37]
	v_mfma_f32_16x16x32_bf16 v[22:25], v[170:173], v[202:205], v[22:25]
	v_mfma_f32_16x16x32_bf16 v[18:21], v[178:181], v[202:205], v[18:21]
	v_mfma_f32_16x16x32_bf16 v[6:9], v[170:173], v[210:213], v[6:9]
	v_mfma_f32_16x16x32_bf16 v[2:5], v[178:181], v[210:213], v[2:5]
	s_barrier
	s_add_i32 s56, 0, 0x18000
	s_add_i32 s57, 0, 0x1c000
	v_add_u32_e32 v162, s56, v159
	v_add_u32_e32 v178, s57, v159
	ds_read_b128 v[130:133], v162
	ds_read_b128 v[134:137], v162 offset:1024
	ds_read_b128 v[148:151], v162 offset:2048
	ds_read_b128 v[162:165], v162 offset:3072
	ds_read_b128 v[166:169], v178
	ds_read_b128 v[170:173], v178 offset:1024
	ds_read_b128 v[174:177], v178 offset:2048
	ds_read_b128 v[178:181], v178 offset:3072
	s_add_u32 s26, s26, 0x100000
	s_addc_u32 s27, s27, 0
	s_mov_b32 m0, s44
	v_lshl_add_u64 v[218:219], s[26:27], 0, v[138:139]
	ds_read_b128 v[182:185], v161 offset:32768
	ds_read_b128 v[186:189], v161 offset:33792
	ds_read_b128 v[190:193], v161 offset:34816
	ds_read_b128 v[194:197], v161 offset:35840
	ds_read_b128 v[198:201], v161 offset:36864
	ds_read_b128 v[202:205], v161 offset:37888
	ds_read_b128 v[206:209], v161 offset:38912
	ds_read_b128 v[210:213], v161 offset:39936
	global_load_lds_dwordx4 v[218:219], off
	v_lshl_add_u64 v[218:219], s[26:27], 0, v[140:141]
	s_mov_b32 m0, s45
	s_nop 0
	global_load_lds_dwordx4 v[218:219], off
	s_waitcnt vmcnt(8)
	s_waitcnt lgkmcnt(0)
	s_barrier
	v_mfma_f32_16x16x32_bf16 v[126:129], v[130:133], v[182:185], v[126:129]
	v_mfma_f32_16x16x32_bf16 v[122:125], v[148:151], v[182:185], v[122:125]
	v_mfma_f32_16x16x32_bf16 v[110:113], v[130:133], v[190:193], v[110:113]
	v_mfma_f32_16x16x32_bf16 v[106:109], v[148:151], v[190:193], v[106:109]
	v_mfma_f32_16x16x32_bf16 v[94:97], v[130:133], v[198:201], v[94:97]
	v_mfma_f32_16x16x32_bf16 v[90:93], v[148:151], v[198:201], v[90:93]
	v_mfma_f32_16x16x32_bf16 v[78:81], v[130:133], v[206:209], v[78:81]
	v_mfma_f32_16x16x32_bf16 v[74:77], v[148:151], v[206:209], v[74:77]
	v_mfma_f32_16x16x32_bf16 v[126:129], v[134:137], v[186:189], v[126:129]
	v_mfma_f32_16x16x32_bf16 v[122:125], v[162:165], v[186:189], v[122:125]
	v_mfma_f32_16x16x32_bf16 v[110:113], v[134:137], v[194:197], v[110:113]
	v_mfma_f32_16x16x32_bf16 v[106:109], v[162:165], v[194:197], v[106:109]
	v_mfma_f32_16x16x32_bf16 v[94:97], v[134:137], v[202:205], v[94:97]
	v_mfma_f32_16x16x32_bf16 v[90:93], v[162:165], v[202:205], v[90:93]
	v_mfma_f32_16x16x32_bf16 v[78:81], v[134:137], v[210:213], v[78:81]
	v_mfma_f32_16x16x32_bf16 v[74:77], v[162:165], v[210:213], v[74:77]
	v_mfma_f32_16x16x32_bf16 v[118:121], v[166:169], v[182:185], v[118:121]
	v_mfma_f32_16x16x32_bf16 v[114:117], v[174:177], v[182:185], v[114:117]
	v_mfma_f32_16x16x32_bf16 v[102:105], v[166:169], v[190:193], v[102:105]
	v_mfma_f32_16x16x32_bf16 v[98:101], v[174:177], v[190:193], v[98:101]
	v_mfma_f32_16x16x32_bf16 v[86:89], v[166:169], v[198:201], v[86:89]
	v_mfma_f32_16x16x32_bf16 v[82:85], v[174:177], v[198:201], v[82:85]
	v_mfma_f32_16x16x32_bf16 v[70:73], v[166:169], v[206:209], v[70:73]
	v_mfma_f32_16x16x32_bf16 v[66:69], v[174:177], v[206:209], v[66:69]
	v_mfma_f32_16x16x32_bf16 v[118:121], v[170:173], v[186:189], v[118:121]
	v_mfma_f32_16x16x32_bf16 v[114:117], v[178:181], v[186:189], v[114:117]
	v_mfma_f32_16x16x32_bf16 v[102:105], v[170:173], v[194:197], v[102:105]
	v_mfma_f32_16x16x32_bf16 v[98:101], v[178:181], v[194:197], v[98:101]
	v_mfma_f32_16x16x32_bf16 v[86:89], v[170:173], v[202:205], v[86:89]
	v_mfma_f32_16x16x32_bf16 v[82:85], v[178:181], v[202:205], v[82:85]
	v_mfma_f32_16x16x32_bf16 v[70:73], v[170:173], v[210:213], v[70:73]
	v_mfma_f32_16x16x32_bf16 v[66:69], v[178:181], v[210:213], v[66:69]
	s_barrier
	s_add_i32 s26, s56, s37
	v_lshl_add_u64 v[152:153], v[152:153], 0, s[62:63]
	s_mov_b32 m0, s26
	ds_read_b128 v[182:185], v161 offset:49152
	ds_read_b128 v[186:189], v161 offset:50176
	ds_read_b128 v[190:193], v161 offset:51200
	ds_read_b128 v[194:197], v161 offset:52224
	ds_read_b128 v[198:201], v161 offset:53248
	ds_read_b128 v[202:205], v161 offset:54272
	ds_read_b128 v[206:209], v161 offset:55296
	ds_read_b128 v[210:213], v161 offset:56320
	global_load_lds_dwordx4 v[152:153], off
	s_add_i32 m0, s26, 0x2000
	s_add_u32 s24, s24, 0x100080
	v_lshl_add_u64 v[152:153], v[156:157], 0, s[62:63]
	s_addc_u32 s25, s25, 0
	s_add_i32 s26, s57, s37
	global_load_lds_dwordx4 v[152:153], off
	v_lshl_add_u64 v[152:153], s[24:25], 0, v[154:155]
	s_mov_b32 m0, s26
	s_nop 0
	global_load_lds_dwordx4 v[152:153], off
	v_lshl_add_u64 v[152:153], s[24:25], 0, v[142:143]
	s_add_i32 m0, s26, 0x2000
	s_nop 0
	global_load_lds_dwordx4 v[152:153], off
	v_lshl_add_u64 v[152:153], v[214:215], 0, s[62:63]
	s_mov_b32 m0, s53
	s_nop 0
	global_load_lds_dwordx4 v[152:153], off
	v_lshl_add_u64 v[152:153], v[216:217], 0, s[62:63]
	s_mov_b32 m0, s55
	s_nop 0
	global_load_lds_dwordx4 v[152:153], off
	s_waitcnt vmcnt(8)
	s_waitcnt lgkmcnt(0)
	s_barrier
	v_mfma_f32_16x16x32_bf16 v[62:65], v[130:133], v[182:185], v[62:65]
	v_mfma_f32_16x16x32_bf16 v[58:61], v[148:151], v[182:185], v[58:61]
	v_mfma_f32_16x16x32_bf16 v[46:49], v[130:133], v[190:193], v[46:49]
	v_mfma_f32_16x16x32_bf16 v[42:45], v[148:151], v[190:193], v[42:45]
	v_mfma_f32_16x16x32_bf16 v[30:33], v[130:133], v[198:201], v[30:33]
	v_mfma_f32_16x16x32_bf16 v[26:29], v[148:151], v[198:201], v[26:29]
	v_mfma_f32_16x16x32_bf16 v[14:17], v[130:133], v[206:209], v[14:17]
	v_mfma_f32_16x16x32_bf16 v[10:13], v[148:151], v[206:209], v[10:13]
	v_mfma_f32_16x16x32_bf16 v[62:65], v[134:137], v[186:189], v[62:65]
	v_mfma_f32_16x16x32_bf16 v[58:61], v[162:165], v[186:189], v[58:61]
	v_mfma_f32_16x16x32_bf16 v[46:49], v[134:137], v[194:197], v[46:49]
	v_mfma_f32_16x16x32_bf16 v[42:45], v[162:165], v[194:197], v[42:45]
	v_mfma_f32_16x16x32_bf16 v[30:33], v[134:137], v[202:205], v[30:33]
	v_mfma_f32_16x16x32_bf16 v[26:29], v[162:165], v[202:205], v[26:29]
	v_mfma_f32_16x16x32_bf16 v[14:17], v[134:137], v[210:213], v[14:17]
	v_mfma_f32_16x16x32_bf16 v[10:13], v[162:165], v[210:213], v[10:13]
	v_mfma_f32_16x16x32_bf16 v[54:57], v[166:169], v[182:185], v[54:57]
	v_mfma_f32_16x16x32_bf16 v[50:53], v[174:177], v[182:185], v[50:53]
	v_mfma_f32_16x16x32_bf16 v[38:41], v[166:169], v[190:193], v[38:41]
	v_mfma_f32_16x16x32_bf16 v[34:37], v[174:177], v[190:193], v[34:37]
	v_mfma_f32_16x16x32_bf16 v[22:25], v[166:169], v[198:201], v[22:25]
	v_mfma_f32_16x16x32_bf16 v[18:21], v[174:177], v[198:201], v[18:21]
	v_mfma_f32_16x16x32_bf16 v[6:9], v[166:169], v[206:209], v[6:9]
	v_mfma_f32_16x16x32_bf16 v[2:5], v[174:177], v[206:209], v[2:5]
	v_mfma_f32_16x16x32_bf16 v[54:57], v[170:173], v[186:189], v[54:57]
	v_mfma_f32_16x16x32_bf16 v[50:53], v[178:181], v[186:189], v[50:53]
	v_mfma_f32_16x16x32_bf16 v[38:41], v[170:173], v[194:197], v[38:41]
	v_mfma_f32_16x16x32_bf16 v[34:37], v[178:181], v[194:197], v[34:37]
	v_mfma_f32_16x16x32_bf16 v[22:25], v[170:173], v[202:205], v[22:25]
	v_mfma_f32_16x16x32_bf16 v[18:21], v[178:181], v[202:205], v[18:21]
	v_mfma_f32_16x16x32_bf16 v[6:9], v[170:173], v[210:213], v[6:9]
	v_mfma_f32_16x16x32_bf16 v[2:5], v[178:181], v[210:213], v[2:5]
	s_barrier
	s_add_i32 s69, s69, 2
	s_add_u32 s22, s22, 0x100
	s_addc_u32 s23, s23, 0
	s_add_u32 s40, s40, 0x100
	s_addc_u32 s68, s68, 0
	s_cmp_gt_u32 s69, 61
	s_cbranch_scc0 .LBB0_534
	v_lshl_add_u32 v148, s20, 8, v158
	v_lshl_or_b32 v150, s18, 8, v160
	v_ashrrev_i32_e32 v149, 31, v148
	v_lshlrev_b64 v[130:131], 11, v[148:149]
	v_ashrrev_i32_e32 v151, 31, v150
	v_lshl_add_u64 v[130:131], s[8:9], 0, v[130:131]
	v_lshlrev_b64 v[132:133], 1, v[150:151]
	v_lshl_add_u64 v[172:173], v[130:131], 0, v[132:133]
	global_load_dwordx4 v[164:167], v[172:173], off
	global_load_dwordx4 v[168:171], v[172:173], off offset:256
	v_or_b32_e32 v152, 16, v148
	v_ashrrev_i32_e32 v153, 31, v152
	v_lshlrev_b64 v[130:131], 11, v[152:153]
	v_lshl_add_u64 v[130:131], s[8:9], 0, v[130:131]
	v_lshl_add_u64 v[156:157], v[130:131], 0, v[132:133]
	global_load_dwordx4 v[134:137], v[156:157], off
	global_load_dwordx4 v[130:133], v[156:157], off offset:256
	v_and_b32_e32 v163, 64, v1
	v_xor_b32_e32 v162, 16, v1
	v_add_u32_e32 v163, 64, v163
	v_xor_b32_e32 v174, 32, v1
	v_cmp_lt_i32_e32 vcc, v162, v163
	s_lshl_b32 s18, s18, 2
	s_ashr_i32 s19, s18, 31
	v_cndmask_b32_e32 v162, v1, v162, vcc
	v_cmp_lt_i32_e32 vcc, v174, v163
	v_lshlrev_b32_e32 v162, 2, v162
	s_waitcnt vmcnt(0)
	v_and_b32_e32 v175, 0xffff0000, v164
	v_cndmask_b32_e32 v163, v1, v174, vcc
	v_lshlrev_b32_e32 v174, 16, v164
	v_lshlrev_b32_e32 v164, 16, v165
	v_and_b32_e32 v165, 0xffff0000, v165
	v_lshlrev_b32_e32 v176, 16, v166
	v_and_b32_e32 v177, 0xffff0000, v166
	v_lshlrev_b32_e32 v166, 16, v167
	v_and_b32_e32 v167, 0xffff0000, v167
	v_lshlrev_b32_e32 v178, 16, v168
	v_and_b32_e32 v179, 0xffff0000, v168
	v_lshlrev_b32_e32 v168, 16, v169
	v_and_b32_e32 v169, 0xffff0000, v169
	v_lshlrev_b32_e32 v180, 16, v170
	v_and_b32_e32 v181, 0xffff0000, v170
	v_lshlrev_b32_e32 v170, 16, v171
	v_and_b32_e32 v171, 0xffff0000, v171
	v_pk_add_f32 v[128:129], v[128:129], v[164:165]
	v_pk_add_f32 v[126:127], v[126:127], v[174:175]
	v_pk_add_f32 v[122:123], v[122:123], v[176:177]
	v_pk_add_f32 v[124:125], v[124:125], v[166:167]
	v_pk_add_f32 v[120:121], v[120:121], v[168:169]
	v_pk_add_f32 v[118:119], v[118:119], v[178:179]
	v_pk_add_f32 v[164:165], v[114:115], v[180:181]
	v_pk_add_f32 v[166:167], v[116:117], v[170:171]
	v_cvt_pk_bf16_f32 v114, v126, v127
	v_cvt_pk_bf16_f32 v115, v128, v129
	v_mul_f32_e32 v116, v126, v126
	v_mul_f32_e32 v117, v128, v128
	v_mul_f32_e32 v126, v122, v122
	v_mul_f32_e32 v128, v125, v125
	v_mul_f32_e32 v168, v118, v118
	v_mul_f32_e32 v169, v120, v120
	v_mul_f32_e32 v170, v164, v164
	v_mul_f32_e32 v171, v167, v167
	v_fmac_f32_e32 v116, v127, v127
	v_fmac_f32_e32 v117, v129, v129
	v_fmac_f32_e32 v126, v123, v123
	v_fmac_f32_e32 v128, v124, v124
	v_fmac_f32_e32 v168, v119, v119
	v_fmac_f32_e32 v169, v121, v121
	v_fmac_f32_e32 v170, v165, v165
	v_fmac_f32_e32 v171, v166, v166
	v_add_f32_e32 v116, v117, v116
	v_add_f32_e32 v117, v128, v126
	v_add_f32_e32 v126, v169, v168
	v_add_f32_e32 v127, v171, v170
	v_add_f32_e32 v116, v117, v116
	v_add_f32_e32 v117, v127, v126
	v_add_f32_e32 v126, v116, v117
	ds_bpermute_b32 v127, v162, v126
	v_cvt_pk_bf16_f32 v116, v122, v123
	v_cvt_pk_bf16_f32 v117, v124, v125
	global_store_dwordx4 v[172:173], v[114:117], off
	s_waitcnt lgkmcnt(0)
	s_nop 0
	v_add_f32_e32 v114, v126, v127
	v_lshlrev_b32_e32 v126, 2, v163
	ds_bpermute_b32 v115, v126, v114
	v_cvt_pk_bf16_f32 v116, v118, v119
	v_cvt_pk_bf16_f32 v117, v120, v121
	v_cvt_pk_bf16_f32 v118, v164, v165
	v_cvt_pk_bf16_f32 v119, v166, v167
	global_store_dwordx4 v[172:173], v[116:119], off offset:256
	s_and_saveexec_b64 s[20:21], s[0:1]
	s_cbranch_execz .LBB0_537
	v_lshlrev_b64 v[116:117], 7, v[148:149]
	v_lshl_add_u64 v[116:117], s[6:7], 0, v[116:117]
	v_lshl_add_u64 v[116:117], s[18:19], 2, v[116:117]
	s_lshl_b32 s40, s51, 2
	v_lshl_add_u64 v[116:117], v[116:117], 0, s[40:41]
	s_waitcnt lgkmcnt(0)
	v_add_f32_e32 v114, v114, v115
	global_store_dword v[116:117], v114, off

.LBB0_631:
	s_add_u32 s28, s26, 0xfffc0080
	s_addc_u32 s29, s27, -1
	s_add_i32 s62, 0, 0x10000
	s_cmp_eq_u32 s61, 12
	s_cselect_b32 s31, s3, s29
	s_cselect_b32 s30, s19, s28
	s_cselect_b32 s29, s17, s60
	s_cselect_b32 s28, s58, s59
	s_add_i32 s64, 0, 0x14000
	v_add_u32_e32 v142, s62, v246
	v_add_u32_e32 v158, s64, v246
	ds_read_b128 v[130:133], v142
	ds_read_b128 v[134:137], v142 offset:1024
	ds_read_b128 v[138:141], v142 offset:2048
	ds_read_b128 v[142:145], v142 offset:3072
	ds_read_b128 v[146:149], v158
	ds_read_b128 v[150:153], v158 offset:1024
	ds_read_b128 v[154:157], v158 offset:2048
	ds_read_b128 v[158:161], v158 offset:3072
	v_lshl_add_u64 v[192:193], s[26:27], 0, v[184:185]
	s_add_i32 m0, s25, 0xc000
	ds_read_b128 v[162:165], v247
	ds_read_b128 v[188:191], v247 offset:1024
	ds_read_b128 v[202:205], v247 offset:2048
	ds_read_b128 v[206:209], v247 offset:3072
	ds_read_b128 v[210:213], v247 offset:4096
	ds_read_b128 v[214:217], v247 offset:5120
	ds_read_b128 v[218:221], v247 offset:6144
	ds_read_b128 v[222:225], v247 offset:7168
	global_load_lds_dwordx4 v[192:193], off
	v_lshl_add_u64 v[192:193], s[26:27], 0, v[186:187]
	s_add_i32 m0, s25, 0xe000
	s_nop 0
	global_load_lds_dwordx4 v[192:193], off
	s_waitcnt vmcnt(8)
	s_waitcnt lgkmcnt(0)
	s_barrier
	v_mfma_f32_16x16x32_bf16 v[126:129], v[130:133], v[162:165], v[126:129]
	v_mfma_f32_16x16x32_bf16 v[122:125], v[138:141], v[162:165], v[122:125]
	v_mfma_f32_16x16x32_bf16 v[110:113], v[130:133], v[202:205], v[110:113]
	v_mfma_f32_16x16x32_bf16 v[106:109], v[138:141], v[202:205], v[106:109]
	v_mfma_f32_16x16x32_bf16 v[94:97], v[130:133], v[210:213], v[94:97]
	v_mfma_f32_16x16x32_bf16 v[90:93], v[138:141], v[210:213], v[90:93]
	v_mfma_f32_16x16x32_bf16 v[78:81], v[130:133], v[218:221], v[78:81]
	v_mfma_f32_16x16x32_bf16 v[74:77], v[138:141], v[218:221], v[74:77]
	v_mfma_f32_16x16x32_bf16 v[126:129], v[134:137], v[188:191], v[126:129]
	v_mfma_f32_16x16x32_bf16 v[122:125], v[142:145], v[188:191], v[122:125]
	v_mfma_f32_16x16x32_bf16 v[110:113], v[134:137], v[206:209], v[110:113]
	v_mfma_f32_16x16x32_bf16 v[106:109], v[142:145], v[206:209], v[106:109]
	v_mfma_f32_16x16x32_bf16 v[94:97], v[134:137], v[214:217], v[94:97]
	v_mfma_f32_16x16x32_bf16 v[90:93], v[142:145], v[214:217], v[90:93]
	v_mfma_f32_16x16x32_bf16 v[78:81], v[134:137], v[222:225], v[78:81]
	v_mfma_f32_16x16x32_bf16 v[74:77], v[142:145], v[222:225], v[74:77]
	v_mfma_f32_16x16x32_bf16 v[118:121], v[146:149], v[162:165], v[118:121]
	v_mfma_f32_16x16x32_bf16 v[114:117], v[154:157], v[162:165], v[114:117]
	v_mfma_f32_16x16x32_bf16 v[102:105], v[146:149], v[202:205], v[102:105]
	v_mfma_f32_16x16x32_bf16 v[98:101], v[154:157], v[202:205], v[98:101]
	v_mfma_f32_16x16x32_bf16 v[86:89], v[146:149], v[210:213], v[86:89]
	v_mfma_f32_16x16x32_bf16 v[82:85], v[154:157], v[210:213], v[82:85]
	v_mfma_f32_16x16x32_bf16 v[70:73], v[146:149], v[218:221], v[70:73]
	v_mfma_f32_16x16x32_bf16 v[66:69], v[154:157], v[218:221], v[66:69]
	v_mfma_f32_16x16x32_bf16 v[118:121], v[150:153], v[188:191], v[118:121]
	v_mfma_f32_16x16x32_bf16 v[114:117], v[158:161], v[188:191], v[114:117]
	v_mfma_f32_16x16x32_bf16 v[102:105], v[150:153], v[206:209], v[102:105]
	v_mfma_f32_16x16x32_bf16 v[98:101], v[158:161], v[206:209], v[98:101]
	v_mfma_f32_16x16x32_bf16 v[86:89], v[150:153], v[214:217], v[86:89]
	v_mfma_f32_16x16x32_bf16 v[82:85], v[158:161], v[214:217], v[82:85]
	v_mfma_f32_16x16x32_bf16 v[70:73], v[150:153], v[222:225], v[70:73]
	v_mfma_f32_16x16x32_bf16 v[66:69], v[158:161], v[222:225], v[66:69]
	s_barrier
	s_add_i32 s62, s62, s45
	v_lshl_add_u64 v[192:193], s[28:29], 0, v[168:169]
	s_mov_b32 m0, s62
	ds_read_b128 v[162:165], v247 offset:16384
	ds_read_b128 v[188:191], v247 offset:17408
	ds_read_b128 v[202:205], v247 offset:18432
	ds_read_b128 v[206:209], v247 offset:19456
	ds_read_b128 v[210:213], v247 offset:20480
	ds_read_b128 v[214:217], v247 offset:21504
	ds_read_b128 v[218:221], v247 offset:22528
	ds_read_b128 v[222:225], v247 offset:23552
	global_load_lds_dwordx4 v[192:193], off
	s_add_i32 m0, s62, 0x2000
	s_add_u32 s62, s28, 0x40000
	v_lshl_add_u64 v[226:227], s[28:29], 0, v[172:173]
	s_addc_u32 s63, s29, 0
	s_add_i32 s64, s64, s45
	global_load_lds_dwordx4 v[226:227], off
	v_lshl_add_u64 v[228:229], s[62:63], 0, v[168:169]
	s_mov_b32 m0, s64
	v_lshl_add_u64 v[248:249], s[30:31], 0, v[170:171]
	global_load_lds_dwordx4 v[228:229], off
	v_lshl_add_u64 v[228:229], s[62:63], 0, v[172:173]
	s_add_i32 m0, s64, 0x2000
	s_nop 0
	global_load_lds_dwordx4 v[228:229], off
	v_lshl_add_u64 v[228:229], s[30:31], 0, v[166:167]
	s_mov_b32 m0, s25
	s_nop 0
	global_load_lds_dwordx4 v[228:229], off
	s_mov_b32 m0, s46
	s_nop 0
	global_load_lds_dwordx4 v[248:249], off
	s_waitcnt vmcnt(8)
	s_waitcnt lgkmcnt(0)
	s_barrier
	v_mfma_f32_16x16x32_bf16 v[62:65], v[130:133], v[162:165], v[62:65]
	v_mfma_f32_16x16x32_bf16 v[58:61], v[138:141], v[162:165], v[58:61]
	v_mfma_f32_16x16x32_bf16 v[46:49], v[130:133], v[202:205], v[46:49]
	v_mfma_f32_16x16x32_bf16 v[42:45], v[138:141], v[202:205], v[42:45]
	v_mfma_f32_16x16x32_bf16 v[30:33], v[130:133], v[210:213], v[30:33]
	v_mfma_f32_16x16x32_bf16 v[26:29], v[138:141], v[210:213], v[26:29]
	v_mfma_f32_16x16x32_bf16 v[14:17], v[130:133], v[218:221], v[14:17]
	v_mfma_f32_16x16x32_bf16 v[10:13], v[138:141], v[218:221], v[10:13]
	v_mfma_f32_16x16x32_bf16 v[62:65], v[134:137], v[188:191], v[62:65]
	v_mfma_f32_16x16x32_bf16 v[58:61], v[142:145], v[188:191], v[58:61]
	v_mfma_f32_16x16x32_bf16 v[46:49], v[134:137], v[206:209], v[46:49]
	v_mfma_f32_16x16x32_bf16 v[42:45], v[142:145], v[206:209], v[42:45]
	v_mfma_f32_16x16x32_bf16 v[30:33], v[134:137], v[214:217], v[30:33]
	v_mfma_f32_16x16x32_bf16 v[26:29], v[142:145], v[214:217], v[26:29]
	v_mfma_f32_16x16x32_bf16 v[14:17], v[134:137], v[222:225], v[14:17]
	v_mfma_f32_16x16x32_bf16 v[10:13], v[142:145], v[222:225], v[10:13]
	v_mfma_f32_16x16x32_bf16 v[54:57], v[146:149], v[162:165], v[54:57]
	v_mfma_f32_16x16x32_bf16 v[50:53], v[154:157], v[162:165], v[50:53]
	v_mfma_f32_16x16x32_bf16 v[38:41], v[146:149], v[202:205], v[38:41]
	v_mfma_f32_16x16x32_bf16 v[34:37], v[154:157], v[202:205], v[34:37]
	v_mfma_f32_16x16x32_bf16 v[22:25], v[146:149], v[210:213], v[22:25]
	v_mfma_f32_16x16x32_bf16 v[18:21], v[154:157], v[210:213], v[18:21]
	v_mfma_f32_16x16x32_bf16 v[6:9], v[146:149], v[218:221], v[6:9]
	v_mfma_f32_16x16x32_bf16 v[2:5], v[154:157], v[218:221], v[2:5]
	v_mfma_f32_16x16x32_bf16 v[54:57], v[150:153], v[188:191], v[54:57]
	v_mfma_f32_16x16x32_bf16 v[50:53], v[158:161], v[188:191], v[50:53]
	v_mfma_f32_16x16x32_bf16 v[38:41], v[150:153], v[206:209], v[38:41]
	v_mfma_f32_16x16x32_bf16 v[34:37], v[158:161], v[206:209], v[34:37]
	v_mfma_f32_16x16x32_bf16 v[22:25], v[150:153], v[214:217], v[22:25]
	v_mfma_f32_16x16x32_bf16 v[18:21], v[158:161], v[214:217], v[18:21]
	v_mfma_f32_16x16x32_bf16 v[6:9], v[150:153], v[222:225], v[6:9]
	v_mfma_f32_16x16x32_bf16 v[2:5], v[158:161], v[222:225], v[2:5]
	s_barrier
	s_add_i32 s62, 0, 0x18000
	s_add_i32 s63, 0, 0x1c000
	v_add_u32_e32 v142, s62, v246
	v_add_u32_e32 v158, s63, v246
	ds_read_b128 v[130:133], v142
	ds_read_b128 v[134:137], v142 offset:1024
	ds_read_b128 v[138:141], v142 offset:2048
	ds_read_b128 v[142:145], v142 offset:3072
	ds_read_b128 v[146:149], v158
	ds_read_b128 v[150:153], v158 offset:1024
	ds_read_b128 v[154:157], v158 offset:2048
	ds_read_b128 v[158:161], v158 offset:3072
	s_add_u32 s30, s30, 0x40000
	s_addc_u32 s31, s31, 0
	s_mov_b32 m0, s47
	v_lshl_add_u64 v[250:251], s[30:31], 0, v[166:167]
	ds_read_b128 v[162:165], v247 offset:32768
	ds_read_b128 v[188:191], v247 offset:33792
	ds_read_b128 v[202:205], v247 offset:34816
	ds_read_b128 v[206:209], v247 offset:35840
	ds_read_b128 v[210:213], v247 offset:36864
	ds_read_b128 v[214:217], v247 offset:37888
	ds_read_b128 v[218:221], v247 offset:38912
	ds_read_b128 v[222:225], v247 offset:39936
	global_load_lds_dwordx4 v[250:251], off
	v_lshl_add_u64 v[250:251], s[30:31], 0, v[170:171]
	s_mov_b32 m0, s48
	s_nop 0
	global_load_lds_dwordx4 v[250:251], off
	s_waitcnt vmcnt(8)
	s_waitcnt lgkmcnt(0)
	s_barrier
	v_mfma_f32_16x16x32_bf16 v[126:129], v[130:133], v[162:165], v[126:129]
	v_mfma_f32_16x16x32_bf16 v[122:125], v[138:141], v[162:165], v[122:125]
	v_mfma_f32_16x16x32_bf16 v[110:113], v[130:133], v[202:205], v[110:113]
	v_mfma_f32_16x16x32_bf16 v[106:109], v[138:141], v[202:205], v[106:109]
	v_mfma_f32_16x16x32_bf16 v[94:97], v[130:133], v[210:213], v[94:97]
	v_mfma_f32_16x16x32_bf16 v[90:93], v[138:141], v[210:213], v[90:93]
	v_mfma_f32_16x16x32_bf16 v[78:81], v[130:133], v[218:221], v[78:81]
	v_mfma_f32_16x16x32_bf16 v[74:77], v[138:141], v[218:221], v[74:77]
	v_mfma_f32_16x16x32_bf16 v[126:129], v[134:137], v[188:191], v[126:129]
	v_mfma_f32_16x16x32_bf16 v[122:125], v[142:145], v[188:191], v[122:125]
	v_mfma_f32_16x16x32_bf16 v[110:113], v[134:137], v[206:209], v[110:113]
	v_mfma_f32_16x16x32_bf16 v[106:109], v[142:145], v[206:209], v[106:109]
	v_mfma_f32_16x16x32_bf16 v[94:97], v[134:137], v[214:217], v[94:97]
	v_mfma_f32_16x16x32_bf16 v[90:93], v[142:145], v[214:217], v[90:93]
	v_mfma_f32_16x16x32_bf16 v[78:81], v[134:137], v[222:225], v[78:81]
	v_mfma_f32_16x16x32_bf16 v[74:77], v[142:145], v[222:225], v[74:77]
	v_mfma_f32_16x16x32_bf16 v[118:121], v[146:149], v[162:165], v[118:121]
	v_mfma_f32_16x16x32_bf16 v[114:117], v[154:157], v[162:165], v[114:117]
	v_mfma_f32_16x16x32_bf16 v[102:105], v[146:149], v[202:205], v[102:105]
	v_mfma_f32_16x16x32_bf16 v[98:101], v[154:157], v[202:205], v[98:101]
	v_mfma_f32_16x16x32_bf16 v[86:89], v[146:149], v[210:213], v[86:89]
	v_mfma_f32_16x16x32_bf16 v[82:85], v[154:157], v[210:213], v[82:85]
	v_mfma_f32_16x16x32_bf16 v[70:73], v[146:149], v[218:221], v[70:73]
	v_mfma_f32_16x16x32_bf16 v[66:69], v[154:157], v[218:221], v[66:69]
	v_mfma_f32_16x16x32_bf16 v[118:121], v[150:153], v[188:191], v[118:121]
	v_mfma_f32_16x16x32_bf16 v[114:117], v[158:161], v[188:191], v[114:117]
	v_mfma_f32_16x16x32_bf16 v[102:105], v[150:153], v[206:209], v[102:105]
	v_mfma_f32_16x16x32_bf16 v[98:101], v[158:161], v[206:209], v[98:101]
	v_mfma_f32_16x16x32_bf16 v[86:89], v[150:153], v[214:217], v[86:89]
	v_mfma_f32_16x16x32_bf16 v[82:85], v[158:161], v[214:217], v[82:85]
	v_mfma_f32_16x16x32_bf16 v[70:73], v[150:153], v[222:225], v[70:73]
	v_mfma_f32_16x16x32_bf16 v[66:69], v[158:161], v[222:225], v[66:69]
	s_barrier
	s_add_i32 s30, s62, s45
	v_lshl_add_u64 v[192:193], v[192:193], 0, s[92:93]
	s_mov_b32 m0, s30
	ds_read_b128 v[162:165], v247 offset:49152
	ds_read_b128 v[188:191], v247 offset:50176
	ds_read_b128 v[202:205], v247 offset:51200
	ds_read_b128 v[206:209], v247 offset:52224
	ds_read_b128 v[210:213], v247 offset:53248
	ds_read_b128 v[214:217], v247 offset:54272
	ds_read_b128 v[218:221], v247 offset:55296
	ds_read_b128 v[222:225], v247 offset:56320
	global_load_lds_dwordx4 v[192:193], off
	s_add_i32 m0, s30, 0x2000
	s_add_u32 s28, s28, 0x40080
	v_lshl_add_u64 v[192:193], v[226:227], 0, s[92:93]
	s_addc_u32 s29, s29, 0
	s_add_i32 s30, s63, s45
	global_load_lds_dwordx4 v[192:193], off
	v_lshl_add_u64 v[192:193], s[28:29], 0, v[168:169]
	s_mov_b32 m0, s30
	s_nop 0
	global_load_lds_dwordx4 v[192:193], off
	v_lshl_add_u64 v[192:193], s[28:29], 0, v[172:173]
	s_add_i32 m0, s30, 0x2000
	s_nop 0
	global_load_lds_dwordx4 v[192:193], off
	v_lshl_add_u64 v[192:193], v[228:229], 0, s[92:93]
	s_mov_b32 m0, s52
	s_nop 0
	global_load_lds_dwordx4 v[192:193], off
	v_lshl_add_u64 v[192:193], v[248:249], 0, s[92:93]
	s_mov_b32 m0, s53
	s_nop 0
	global_load_lds_dwordx4 v[192:193], off
	s_waitcnt vmcnt(8)
	s_waitcnt lgkmcnt(0)
	s_barrier
	v_mfma_f32_16x16x32_bf16 v[62:65], v[130:133], v[162:165], v[62:65]
	v_mfma_f32_16x16x32_bf16 v[58:61], v[138:141], v[162:165], v[58:61]
	v_mfma_f32_16x16x32_bf16 v[46:49], v[130:133], v[202:205], v[46:49]
	v_mfma_f32_16x16x32_bf16 v[42:45], v[138:141], v[202:205], v[42:45]
	v_mfma_f32_16x16x32_bf16 v[30:33], v[130:133], v[210:213], v[30:33]
	v_mfma_f32_16x16x32_bf16 v[26:29], v[138:141], v[210:213], v[26:29]
	v_mfma_f32_16x16x32_bf16 v[14:17], v[130:133], v[218:221], v[14:17]
	v_mfma_f32_16x16x32_bf16 v[10:13], v[138:141], v[218:221], v[10:13]
	v_mfma_f32_16x16x32_bf16 v[62:65], v[134:137], v[188:191], v[62:65]
	v_mfma_f32_16x16x32_bf16 v[58:61], v[142:145], v[188:191], v[58:61]
	v_mfma_f32_16x16x32_bf16 v[46:49], v[134:137], v[206:209], v[46:49]
	v_mfma_f32_16x16x32_bf16 v[42:45], v[142:145], v[206:209], v[42:45]
	v_mfma_f32_16x16x32_bf16 v[30:33], v[134:137], v[214:217], v[30:33]
	v_mfma_f32_16x16x32_bf16 v[26:29], v[142:145], v[214:217], v[26:29]
	v_mfma_f32_16x16x32_bf16 v[14:17], v[134:137], v[222:225], v[14:17]
	v_mfma_f32_16x16x32_bf16 v[10:13], v[142:145], v[222:225], v[10:13]
	v_mfma_f32_16x16x32_bf16 v[54:57], v[146:149], v[162:165], v[54:57]
	v_mfma_f32_16x16x32_bf16 v[50:53], v[154:157], v[162:165], v[50:53]
	v_mfma_f32_16x16x32_bf16 v[38:41], v[146:149], v[202:205], v[38:41]
	v_mfma_f32_16x16x32_bf16 v[34:37], v[154:157], v[202:205], v[34:37]
	v_mfma_f32_16x16x32_bf16 v[22:25], v[146:149], v[210:213], v[22:25]
	v_mfma_f32_16x16x32_bf16 v[18:21], v[154:157], v[210:213], v[18:21]
	v_mfma_f32_16x16x32_bf16 v[6:9], v[146:149], v[218:221], v[6:9]
	v_mfma_f32_16x16x32_bf16 v[2:5], v[154:157], v[218:221], v[2:5]
	v_mfma_f32_16x16x32_bf16 v[54:57], v[150:153], v[188:191], v[54:57]
	v_mfma_f32_16x16x32_bf16 v[50:53], v[158:161], v[188:191], v[50:53]
	v_mfma_f32_16x16x32_bf16 v[38:41], v[150:153], v[206:209], v[38:41]
	v_mfma_f32_16x16x32_bf16 v[34:37], v[158:161], v[206:209], v[34:37]
	v_mfma_f32_16x16x32_bf16 v[22:25], v[150:153], v[214:217], v[22:25]
	v_mfma_f32_16x16x32_bf16 v[18:21], v[158:161], v[214:217], v[18:21]
	v_mfma_f32_16x16x32_bf16 v[6:9], v[150:153], v[222:225], v[6:9]
	v_mfma_f32_16x16x32_bf16 v[2:5], v[158:161], v[222:225], v[2:5]
	s_barrier
	s_add_i32 s61, s61, 2
	s_add_u32 s26, s26, 0x100
	s_addc_u32 s27, s27, 0
	s_add_u32 s59, s59, 0x100
	s_addc_u32 s60, s60, 0
	s_cmp_gt_u32 s61, 13
	s_cbranch_scc0 .LBB0_631
	s_and_b64 vcc, exec, s[14:15]
	s_cbranch_vccnz .LBB0_636
	s_cmp_gt_i32 s2, 4
	s_mov_b64 s[26:27], -1
	s_cbranch_scc0 .LBB0_637

.LBB0_939:
	s_add_u32 s24, s22, 0xfffc0080
	s_addc_u32 s25, s23, -1
	s_add_i32 s52, 0, 0x10000
	s_cmp_eq_u32 s51, 12
	s_cselect_b32 s27, s13, s25
	s_cselect_b32 s26, s19, s24
	s_cselect_b32 s25, s11, s50
	s_cselect_b32 s24, s21, s49
	s_add_i32 s54, 0, 0x14000
	v_add_u32_e32 v142, s52, v167
	v_add_u32_e32 v164, s54, v167
	ds_read_b128 v[130:133], v142
	ds_read_b128 v[134:137], v142 offset:1024
	ds_read_b128 v[138:141], v142 offset:2048
	ds_read_b128 v[142:145], v142 offset:3072
	ds_read_b128 v[156:159], v164
	ds_read_b128 v[160:163], v164 offset:1024
	ds_read_b128 v[170:173], v164 offset:2048
	ds_read_b128 v[174:177], v164 offset:3072
	v_lshl_add_u64 v[164:165], s[22:23], 0, v[152:153]
	s_add_i32 m0, s38, 0xc000
	ds_read_b128 v[178:181], v169
	ds_read_b128 v[182:185], v169 offset:1024
	ds_read_b128 v[186:189], v169 offset:2048
	ds_read_b128 v[190:193], v169 offset:3072
	ds_read_b128 v[202:205], v169 offset:4096
	ds_read_b128 v[206:209], v169 offset:5120
	ds_read_b128 v[210:213], v169 offset:6144
	ds_read_b128 v[214:217], v169 offset:7168
	global_load_lds_dwordx4 v[164:165], off
	v_lshl_add_u64 v[164:165], s[22:23], 0, v[154:155]
	s_add_i32 m0, s38, 0xe000
	s_nop 0
	global_load_lds_dwordx4 v[164:165], off
	s_waitcnt vmcnt(8)
	s_waitcnt lgkmcnt(0)
	s_barrier
	v_mfma_f32_16x16x32_bf16 v[126:129], v[130:133], v[178:181], v[126:129]
	v_mfma_f32_16x16x32_bf16 v[122:125], v[138:141], v[178:181], v[122:125]
	v_mfma_f32_16x16x32_bf16 v[110:113], v[130:133], v[186:189], v[110:113]
	v_mfma_f32_16x16x32_bf16 v[106:109], v[138:141], v[186:189], v[106:109]
	v_mfma_f32_16x16x32_bf16 v[94:97], v[130:133], v[202:205], v[94:97]
	v_mfma_f32_16x16x32_bf16 v[90:93], v[138:141], v[202:205], v[90:93]
	v_mfma_f32_16x16x32_bf16 v[78:81], v[130:133], v[210:213], v[78:81]
	v_mfma_f32_16x16x32_bf16 v[74:77], v[138:141], v[210:213], v[74:77]
	v_mfma_f32_16x16x32_bf16 v[126:129], v[134:137], v[182:185], v[126:129]
	v_mfma_f32_16x16x32_bf16 v[122:125], v[142:145], v[182:185], v[122:125]
	v_mfma_f32_16x16x32_bf16 v[110:113], v[134:137], v[190:193], v[110:113]
	v_mfma_f32_16x16x32_bf16 v[106:109], v[142:145], v[190:193], v[106:109]
	v_mfma_f32_16x16x32_bf16 v[94:97], v[134:137], v[206:209], v[94:97]
	v_mfma_f32_16x16x32_bf16 v[90:93], v[142:145], v[206:209], v[90:93]
	v_mfma_f32_16x16x32_bf16 v[78:81], v[134:137], v[214:217], v[78:81]
	v_mfma_f32_16x16x32_bf16 v[74:77], v[142:145], v[214:217], v[74:77]
	v_mfma_f32_16x16x32_bf16 v[118:121], v[156:159], v[178:181], v[118:121]
	v_mfma_f32_16x16x32_bf16 v[114:117], v[170:173], v[178:181], v[114:117]
	v_mfma_f32_16x16x32_bf16 v[102:105], v[156:159], v[186:189], v[102:105]
	v_mfma_f32_16x16x32_bf16 v[98:101], v[170:173], v[186:189], v[98:101]
	v_mfma_f32_16x16x32_bf16 v[86:89], v[156:159], v[202:205], v[86:89]
	v_mfma_f32_16x16x32_bf16 v[82:85], v[170:173], v[202:205], v[82:85]
	v_mfma_f32_16x16x32_bf16 v[70:73], v[156:159], v[210:213], v[70:73]
	v_mfma_f32_16x16x32_bf16 v[66:69], v[170:173], v[210:213], v[66:69]
	v_mfma_f32_16x16x32_bf16 v[118:121], v[160:163], v[182:185], v[118:121]
	v_mfma_f32_16x16x32_bf16 v[114:117], v[174:177], v[182:185], v[114:117]
	v_mfma_f32_16x16x32_bf16 v[102:105], v[160:163], v[190:193], v[102:105]
	v_mfma_f32_16x16x32_bf16 v[98:101], v[174:177], v[190:193], v[98:101]
	v_mfma_f32_16x16x32_bf16 v[86:89], v[160:163], v[206:209], v[86:89]
	v_mfma_f32_16x16x32_bf16 v[82:85], v[174:177], v[206:209], v[82:85]
	v_mfma_f32_16x16x32_bf16 v[70:73], v[160:163], v[214:217], v[70:73]
	v_mfma_f32_16x16x32_bf16 v[66:69], v[174:177], v[214:217], v[66:69]
	s_barrier
	s_add_i32 s52, s52, s37
	v_lshl_add_u64 v[164:165], s[24:25], 0, v[194:195]
	s_mov_b32 m0, s52
	ds_read_b128 v[178:181], v169 offset:16384
	ds_read_b128 v[182:185], v169 offset:17408
	ds_read_b128 v[186:189], v169 offset:18432
	ds_read_b128 v[190:193], v169 offset:19456
	ds_read_b128 v[202:205], v169 offset:20480
	ds_read_b128 v[206:209], v169 offset:21504
	ds_read_b128 v[210:213], v169 offset:22528
	ds_read_b128 v[214:217], v169 offset:23552
	global_load_lds_dwordx4 v[164:165], off
	s_add_i32 m0, s52, 0x2000
	s_add_u32 s52, s24, 0x40000
	v_lshl_add_u64 v[218:219], s[24:25], 0, v[150:151]
	s_addc_u32 s53, s25, 0
	s_add_i32 s54, s54, s37
	global_load_lds_dwordx4 v[218:219], off
	v_lshl_add_u64 v[220:221], s[52:53], 0, v[194:195]
	s_mov_b32 m0, s54
	v_lshl_add_u64 v[222:223], s[26:27], 0, v[148:149]
	global_load_lds_dwordx4 v[220:221], off
	v_lshl_add_u64 v[220:221], s[52:53], 0, v[150:151]
	s_add_i32 m0, s54, 0x2000
	s_nop 0
	global_load_lds_dwordx4 v[220:221], off
	v_lshl_add_u64 v[220:221], s[26:27], 0, v[146:147]
	s_mov_b32 m0, s38
	s_nop 0
	global_load_lds_dwordx4 v[220:221], off
	s_mov_b32 m0, s39
	s_nop 0
	global_load_lds_dwordx4 v[222:223], off
	s_waitcnt vmcnt(8)
	s_waitcnt lgkmcnt(0)
	s_barrier
	v_mfma_f32_16x16x32_bf16 v[62:65], v[130:133], v[178:181], v[62:65]
	v_mfma_f32_16x16x32_bf16 v[58:61], v[138:141], v[178:181], v[58:61]
	v_mfma_f32_16x16x32_bf16 v[46:49], v[130:133], v[186:189], v[46:49]
	v_mfma_f32_16x16x32_bf16 v[42:45], v[138:141], v[186:189], v[42:45]
	v_mfma_f32_16x16x32_bf16 v[30:33], v[130:133], v[202:205], v[30:33]
	v_mfma_f32_16x16x32_bf16 v[26:29], v[138:141], v[202:205], v[26:29]
	v_mfma_f32_16x16x32_bf16 v[14:17], v[130:133], v[210:213], v[14:17]
	v_mfma_f32_16x16x32_bf16 v[10:13], v[138:141], v[210:213], v[10:13]
	v_mfma_f32_16x16x32_bf16 v[62:65], v[134:137], v[182:185], v[62:65]
	v_mfma_f32_16x16x32_bf16 v[58:61], v[142:145], v[182:185], v[58:61]
	v_mfma_f32_16x16x32_bf16 v[46:49], v[134:137], v[190:193], v[46:49]
	v_mfma_f32_16x16x32_bf16 v[42:45], v[142:145], v[190:193], v[42:45]
	v_mfma_f32_16x16x32_bf16 v[30:33], v[134:137], v[206:209], v[30:33]
	v_mfma_f32_16x16x32_bf16 v[26:29], v[142:145], v[206:209], v[26:29]
	v_mfma_f32_16x16x32_bf16 v[14:17], v[134:137], v[214:217], v[14:17]
	v_mfma_f32_16x16x32_bf16 v[10:13], v[142:145], v[214:217], v[10:13]
	v_mfma_f32_16x16x32_bf16 v[54:57], v[156:159], v[178:181], v[54:57]
	v_mfma_f32_16x16x32_bf16 v[50:53], v[170:173], v[178:181], v[50:53]
	v_mfma_f32_16x16x32_bf16 v[38:41], v[156:159], v[186:189], v[38:41]
	v_mfma_f32_16x16x32_bf16 v[34:37], v[170:173], v[186:189], v[34:37]
	v_mfma_f32_16x16x32_bf16 v[22:25], v[156:159], v[202:205], v[22:25]
	v_mfma_f32_16x16x32_bf16 v[18:21], v[170:173], v[202:205], v[18:21]
	v_mfma_f32_16x16x32_bf16 v[6:9], v[156:159], v[210:213], v[6:9]
	v_mfma_f32_16x16x32_bf16 v[2:5], v[170:173], v[210:213], v[2:5]
	v_mfma_f32_16x16x32_bf16 v[54:57], v[160:163], v[182:185], v[54:57]
	v_mfma_f32_16x16x32_bf16 v[50:53], v[174:177], v[182:185], v[50:53]
	v_mfma_f32_16x16x32_bf16 v[38:41], v[160:163], v[190:193], v[38:41]
	v_mfma_f32_16x16x32_bf16 v[34:37], v[174:177], v[190:193], v[34:37]
	v_mfma_f32_16x16x32_bf16 v[22:25], v[160:163], v[206:209], v[22:25]
	v_mfma_f32_16x16x32_bf16 v[18:21], v[174:177], v[206:209], v[18:21]
	v_mfma_f32_16x16x32_bf16 v[6:9], v[160:163], v[214:217], v[6:9]
	v_mfma_f32_16x16x32_bf16 v[2:5], v[174:177], v[214:217], v[2:5]
	s_barrier
	s_add_i32 s52, 0, 0x18000
	s_add_i32 s53, 0, 0x1c000
	v_add_u32_e32 v142, s52, v167
	v_add_u32_e32 v174, s53, v167
	ds_read_b128 v[130:133], v142
	ds_read_b128 v[134:137], v142 offset:1024
	ds_read_b128 v[138:141], v142 offset:2048
	ds_read_b128 v[142:145], v142 offset:3072
	ds_read_b128 v[156:159], v174
	ds_read_b128 v[160:163], v174 offset:1024
	ds_read_b128 v[170:173], v174 offset:2048
	ds_read_b128 v[174:177], v174 offset:3072
	s_add_u32 s26, s26, 0x40000
	s_addc_u32 s27, s27, 0
	s_mov_b32 m0, s42
	v_lshl_add_u64 v[224:225], s[26:27], 0, v[146:147]
	ds_read_b128 v[178:181], v169 offset:32768
	ds_read_b128 v[182:185], v169 offset:33792
	ds_read_b128 v[186:189], v169 offset:34816
	ds_read_b128 v[190:193], v169 offset:35840
	ds_read_b128 v[202:205], v169 offset:36864
	ds_read_b128 v[206:209], v169 offset:37888
	ds_read_b128 v[210:213], v169 offset:38912
	ds_read_b128 v[214:217], v169 offset:39936
	global_load_lds_dwordx4 v[224:225], off
	v_lshl_add_u64 v[224:225], s[26:27], 0, v[148:149]
	s_mov_b32 m0, s43
	s_nop 0
	global_load_lds_dwordx4 v[224:225], off
	s_waitcnt vmcnt(8)
	s_waitcnt lgkmcnt(0)
	s_barrier
	v_mfma_f32_16x16x32_bf16 v[126:129], v[130:133], v[178:181], v[126:129]
	v_mfma_f32_16x16x32_bf16 v[122:125], v[138:141], v[178:181], v[122:125]
	v_mfma_f32_16x16x32_bf16 v[110:113], v[130:133], v[186:189], v[110:113]
	v_mfma_f32_16x16x32_bf16 v[106:109], v[138:141], v[186:189], v[106:109]
	v_mfma_f32_16x16x32_bf16 v[94:97], v[130:133], v[202:205], v[94:97]
	v_mfma_f32_16x16x32_bf16 v[90:93], v[138:141], v[202:205], v[90:93]
	v_mfma_f32_16x16x32_bf16 v[78:81], v[130:133], v[210:213], v[78:81]
	v_mfma_f32_16x16x32_bf16 v[74:77], v[138:141], v[210:213], v[74:77]
	v_mfma_f32_16x16x32_bf16 v[126:129], v[134:137], v[182:185], v[126:129]
	v_mfma_f32_16x16x32_bf16 v[122:125], v[142:145], v[182:185], v[122:125]
	v_mfma_f32_16x16x32_bf16 v[110:113], v[134:137], v[190:193], v[110:113]
	v_mfma_f32_16x16x32_bf16 v[106:109], v[142:145], v[190:193], v[106:109]
	v_mfma_f32_16x16x32_bf16 v[94:97], v[134:137], v[206:209], v[94:97]
	v_mfma_f32_16x16x32_bf16 v[90:93], v[142:145], v[206:209], v[90:93]
	v_mfma_f32_16x16x32_bf16 v[78:81], v[134:137], v[214:217], v[78:81]
	v_mfma_f32_16x16x32_bf16 v[74:77], v[142:145], v[214:217], v[74:77]
	v_mfma_f32_16x16x32_bf16 v[118:121], v[156:159], v[178:181], v[118:121]
	v_mfma_f32_16x16x32_bf16 v[114:117], v[170:173], v[178:181], v[114:117]
	v_mfma_f32_16x16x32_bf16 v[102:105], v[156:159], v[186:189], v[102:105]
	v_mfma_f32_16x16x32_bf16 v[98:101], v[170:173], v[186:189], v[98:101]
	v_mfma_f32_16x16x32_bf16 v[86:89], v[156:159], v[202:205], v[86:89]
	v_mfma_f32_16x16x32_bf16 v[82:85], v[170:173], v[202:205], v[82:85]
	v_mfma_f32_16x16x32_bf16 v[70:73], v[156:159], v[210:213], v[70:73]
	v_mfma_f32_16x16x32_bf16 v[66:69], v[170:173], v[210:213], v[66:69]
	v_mfma_f32_16x16x32_bf16 v[118:121], v[160:163], v[182:185], v[118:121]
	v_mfma_f32_16x16x32_bf16 v[114:117], v[174:177], v[182:185], v[114:117]
	v_mfma_f32_16x16x32_bf16 v[102:105], v[160:163], v[190:193], v[102:105]
	v_mfma_f32_16x16x32_bf16 v[98:101], v[174:177], v[190:193], v[98:101]
	v_mfma_f32_16x16x32_bf16 v[86:89], v[160:163], v[206:209], v[86:89]
	v_mfma_f32_16x16x32_bf16 v[82:85], v[174:177], v[206:209], v[82:85]
	v_mfma_f32_16x16x32_bf16 v[70:73], v[160:163], v[214:217], v[70:73]
	v_mfma_f32_16x16x32_bf16 v[66:69], v[174:177], v[214:217], v[66:69]
	s_barrier
	s_add_i32 s26, s52, s37
	v_lshl_add_u64 v[164:165], v[164:165], 0, s[92:93]
	s_mov_b32 m0, s26
	ds_read_b128 v[178:181], v169 offset:49152
	ds_read_b128 v[182:185], v169 offset:50176
	ds_read_b128 v[186:189], v169 offset:51200
	ds_read_b128 v[190:193], v169 offset:52224
	ds_read_b128 v[202:205], v169 offset:53248
	ds_read_b128 v[206:209], v169 offset:54272
	ds_read_b128 v[210:213], v169 offset:55296
	ds_read_b128 v[214:217], v169 offset:56320
	global_load_lds_dwordx4 v[164:165], off
	s_add_i32 m0, s26, 0x2000
	s_add_u32 s24, s24, 0x40080
	v_lshl_add_u64 v[164:165], v[218:219], 0, s[92:93]
	s_addc_u32 s25, s25, 0
	s_add_i32 s26, s53, s37
	global_load_lds_dwordx4 v[164:165], off
	v_lshl_add_u64 v[164:165], s[24:25], 0, v[194:195]
	s_mov_b32 m0, s26
	s_nop 0
	global_load_lds_dwordx4 v[164:165], off
	v_lshl_add_u64 v[164:165], s[24:25], 0, v[150:151]
	s_add_i32 m0, s26, 0x2000
	s_nop 0
	global_load_lds_dwordx4 v[164:165], off
	v_lshl_add_u64 v[164:165], v[220:221], 0, s[92:93]
	s_mov_b32 m0, s45
	s_nop 0
	global_load_lds_dwordx4 v[164:165], off
	v_lshl_add_u64 v[164:165], v[222:223], 0, s[92:93]
	s_mov_b32 m0, s46
	s_nop 0
	global_load_lds_dwordx4 v[164:165], off
	s_waitcnt vmcnt(8)
	s_waitcnt lgkmcnt(0)
	s_barrier
	v_mfma_f32_16x16x32_bf16 v[62:65], v[130:133], v[178:181], v[62:65]
	v_mfma_f32_16x16x32_bf16 v[58:61], v[138:141], v[178:181], v[58:61]
	v_mfma_f32_16x16x32_bf16 v[46:49], v[130:133], v[186:189], v[46:49]
	v_mfma_f32_16x16x32_bf16 v[42:45], v[138:141], v[186:189], v[42:45]
	v_mfma_f32_16x16x32_bf16 v[30:33], v[130:133], v[202:205], v[30:33]
	v_mfma_f32_16x16x32_bf16 v[26:29], v[138:141], v[202:205], v[26:29]
	v_mfma_f32_16x16x32_bf16 v[14:17], v[130:133], v[210:213], v[14:17]
	v_mfma_f32_16x16x32_bf16 v[10:13], v[138:141], v[210:213], v[10:13]
	v_mfma_f32_16x16x32_bf16 v[62:65], v[134:137], v[182:185], v[62:65]
	v_mfma_f32_16x16x32_bf16 v[58:61], v[142:145], v[182:185], v[58:61]
	v_mfma_f32_16x16x32_bf16 v[46:49], v[134:137], v[190:193], v[46:49]
	v_mfma_f32_16x16x32_bf16 v[42:45], v[142:145], v[190:193], v[42:45]
	v_mfma_f32_16x16x32_bf16 v[30:33], v[134:137], v[206:209], v[30:33]
	v_mfma_f32_16x16x32_bf16 v[26:29], v[142:145], v[206:209], v[26:29]
	v_mfma_f32_16x16x32_bf16 v[14:17], v[134:137], v[214:217], v[14:17]
	v_mfma_f32_16x16x32_bf16 v[10:13], v[142:145], v[214:217], v[10:13]
	v_mfma_f32_16x16x32_bf16 v[54:57], v[156:159], v[178:181], v[54:57]
	v_mfma_f32_16x16x32_bf16 v[50:53], v[170:173], v[178:181], v[50:53]
	v_mfma_f32_16x16x32_bf16 v[38:41], v[156:159], v[186:189], v[38:41]
	v_mfma_f32_16x16x32_bf16 v[34:37], v[170:173], v[186:189], v[34:37]
	v_mfma_f32_16x16x32_bf16 v[22:25], v[156:159], v[202:205], v[22:25]
	v_mfma_f32_16x16x32_bf16 v[18:21], v[170:173], v[202:205], v[18:21]
	v_mfma_f32_16x16x32_bf16 v[6:9], v[156:159], v[210:213], v[6:9]
	v_mfma_f32_16x16x32_bf16 v[2:5], v[170:173], v[210:213], v[2:5]
	v_mfma_f32_16x16x32_bf16 v[54:57], v[160:163], v[182:185], v[54:57]
	v_mfma_f32_16x16x32_bf16 v[50:53], v[174:177], v[182:185], v[50:53]
	v_mfma_f32_16x16x32_bf16 v[38:41], v[160:163], v[190:193], v[38:41]
	v_mfma_f32_16x16x32_bf16 v[34:37], v[174:177], v[190:193], v[34:37]
	v_mfma_f32_16x16x32_bf16 v[22:25], v[160:163], v[206:209], v[22:25]
	v_mfma_f32_16x16x32_bf16 v[18:21], v[174:177], v[206:209], v[18:21]
	v_mfma_f32_16x16x32_bf16 v[6:9], v[160:163], v[214:217], v[6:9]
	v_mfma_f32_16x16x32_bf16 v[2:5], v[174:177], v[214:217], v[2:5]
	s_barrier
	s_add_i32 s51, s51, 2
	s_add_u32 s22, s22, 0x100
	s_addc_u32 s23, s23, 0
	s_add_u32 s49, s49, 0x100
	s_addc_u32 s50, s50, 0
	s_cmp_gt_u32 s51, 13
	s_cbranch_scc0 .LBB0_939
	v_lshl_add_u32 v156, s20, 8, v166
	v_lshl_or_b32 v158, s18, 8, v168
	v_ashrrev_i32_e32 v157, 31, v156
	v_lshlrev_b64 v[130:131], 11, v[156:157]
	v_ashrrev_i32_e32 v159, 31, v158
	v_lshl_add_u64 v[130:131], s[8:9], 0, v[130:131]
	v_lshlrev_b64 v[132:133], 1, v[158:159]
	v_lshl_add_u64 v[164:165], v[130:131], 0, v[132:133]
	global_load_dwordx4 v[142:145], v[164:165], off
	global_load_dwordx4 v[138:141], v[164:165], off offset:256
	v_or_b32_e32 v160, 16, v156
	v_ashrrev_i32_e32 v161, 31, v160
	v_lshlrev_b64 v[130:131], 11, v[160:161]
	v_lshl_add_u64 v[130:131], s[8:9], 0, v[130:131]
	v_lshl_add_u64 v[162:163], v[130:131], 0, v[132:133]
	global_load_dwordx4 v[134:137], v[162:163], off
	global_load_dwordx4 v[130:133], v[162:163], off offset:256
	v_and_b32_e32 v171, 64, v1
	v_xor_b32_e32 v170, 16, v1
	v_add_u32_e32 v171, 64, v171
	v_xor_b32_e32 v172, 32, v1
	v_cmp_lt_i32_e32 vcc, v170, v171
	s_lshl_b32 s18, s18, 2
	s_ashr_i32 s19, s18, 31
	v_cndmask_b32_e32 v170, v1, v170, vcc
	v_cmp_lt_i32_e32 vcc, v172, v171
	v_lshlrev_b32_e32 v170, 2, v170
	s_waitcnt vmcnt(0)
	v_and_b32_e32 v173, 0xffff0000, v142
	v_cndmask_b32_e32 v171, v1, v172, vcc
	v_lshlrev_b32_e32 v172, 16, v142
	v_lshlrev_b32_e32 v142, 16, v143
	v_and_b32_e32 v143, 0xffff0000, v143
	v_lshlrev_b32_e32 v174, 16, v144
	v_and_b32_e32 v175, 0xffff0000, v144
	v_lshlrev_b32_e32 v144, 16, v145
	v_and_b32_e32 v145, 0xffff0000, v145
	v_lshlrev_b32_e32 v176, 16, v138
	v_and_b32_e32 v177, 0xffff0000, v138
	v_lshlrev_b32_e32 v138, 16, v139
	v_and_b32_e32 v139, 0xffff0000, v139
	v_lshlrev_b32_e32 v178, 16, v140
	v_and_b32_e32 v179, 0xffff0000, v140
	v_lshlrev_b32_e32 v140, 16, v141
	v_and_b32_e32 v141, 0xffff0000, v141
	v_pk_add_f32 v[128:129], v[128:129], v[142:143]
	v_pk_add_f32 v[126:127], v[126:127], v[172:173]
	v_pk_add_f32 v[122:123], v[122:123], v[174:175]
	v_pk_add_f32 v[124:125], v[124:125], v[144:145]
	v_pk_add_f32 v[120:121], v[120:121], v[138:139]
	v_pk_add_f32 v[118:119], v[118:119], v[176:177]
	v_pk_add_f32 v[138:139], v[114:115], v[178:179]
	v_pk_add_f32 v[140:141], v[116:117], v[140:141]
	v_cvt_pk_bf16_f32 v114, v126, v127
	v_cvt_pk_bf16_f32 v115, v128, v129
	v_mul_f32_e32 v116, v126, v126
	v_mul_f32_e32 v117, v128, v128
	v_mul_f32_e32 v126, v122, v122
	v_mul_f32_e32 v128, v125, v125
	v_mul_f32_e32 v142, v118, v118
	v_mul_f32_e32 v143, v120, v120
	v_mul_f32_e32 v144, v138, v138
	v_mul_f32_e32 v145, v141, v141
	v_fmac_f32_e32 v116, v127, v127
	v_fmac_f32_e32 v117, v129, v129
	v_fmac_f32_e32 v126, v123, v123
	v_fmac_f32_e32 v128, v124, v124
	v_fmac_f32_e32 v142, v119, v119
	v_fmac_f32_e32 v143, v121, v121
	v_fmac_f32_e32 v144, v139, v139
	v_fmac_f32_e32 v145, v140, v140
	v_add_f32_e32 v116, v117, v116
	v_add_f32_e32 v117, v128, v126
	v_add_f32_e32 v126, v143, v142
	v_add_f32_e32 v127, v145, v144
	v_add_f32_e32 v116, v117, v116
	v_add_f32_e32 v117, v127, v126
	v_add_f32_e32 v126, v116, v117
	ds_bpermute_b32 v127, v170, v126
	v_cvt_pk_bf16_f32 v116, v122, v123
	v_cvt_pk_bf16_f32 v117, v124, v125
	global_store_dwordx4 v[164:165], v[114:117], off
	s_waitcnt lgkmcnt(0)
	s_nop 0
	v_add_f32_e32 v114, v126, v127
	v_lshlrev_b32_e32 v126, 2, v171
	ds_bpermute_b32 v115, v126, v114
	v_cvt_pk_bf16_f32 v116, v118, v119
	v_cvt_pk_bf16_f32 v117, v120, v121
	v_cvt_pk_bf16_f32 v118, v138, v139
	v_cvt_pk_bf16_f32 v119, v140, v141
	global_store_dwordx4 v[164:165], v[116:119], off offset:256
	s_and_saveexec_b64 s[20:21], s[0:1]
	s_cbranch_execz .LBB0_942
	v_lshlrev_b64 v[116:117], 7, v[156:157]
	v_lshl_add_u64 v[116:117], s[6:7], 0, v[116:117]
	v_lshl_add_u64 v[116:117], s[18:19], 2, v[116:117]
	s_lshl_b32 s94, s44, 2
	v_lshl_add_u64 v[116:117], v[116:117], 0, s[94:95]
	s_waitcnt lgkmcnt(0)
	v_add_f32_e32 v114, v114, v115
	global_store_dword v[116:117], v114, off

.LBB0_1040:
	s_add_u32 s22, s20, 0xfffc0080
	s_addc_u32 s23, s21, -1
	s_add_i32 s51, 0, 0x10000
	s_cmp_eq_u32 s50, 12
	s_cselect_b32 s25, s13, s23
	s_cselect_b32 s24, s46, s22
	s_cselect_b32 s23, s11, s49
	s_cselect_b32 s22, s47, s48
	s_add_i32 s54, 0, 0x14000
	v_add_u32_e32 v156, s51, v145
	v_add_u32_e32 v172, s54, v145
	ds_read_b128 v[140:143], v156
	ds_read_b128 v[148:151], v156 offset:1024
	ds_read_b128 v[152:155], v156 offset:2048
	ds_read_b128 v[156:159], v156 offset:3072
	ds_read_b128 v[160:163], v172
	ds_read_b128 v[164:167], v172 offset:1024
	ds_read_b128 v[168:171], v172 offset:2048
	ds_read_b128 v[172:175], v172 offset:3072
	v_lshl_add_u64 v[192:193], s[20:21], 0, v[136:137]
	s_add_i32 m0, s19, 0xc000
	ds_read_b128 v[176:179], v147
	ds_read_b128 v[180:183], v147 offset:1024
	ds_read_b128 v[184:187], v147 offset:2048
	ds_read_b128 v[188:191], v147 offset:3072
	ds_read_b128 v[202:205], v147 offset:4096
	ds_read_b128 v[206:209], v147 offset:5120
	ds_read_b128 v[210:213], v147 offset:6144
	ds_read_b128 v[214:217], v147 offset:7168
	global_load_lds_dwordx4 v[192:193], off
	v_lshl_add_u64 v[192:193], s[20:21], 0, v[138:139]
	s_add_i32 m0, s19, 0xe000
	s_nop 0
	global_load_lds_dwordx4 v[192:193], off
	s_waitcnt vmcnt(8)
	s_waitcnt lgkmcnt(0)
	s_barrier
	v_mfma_f32_16x16x32_bf16 v[126:129], v[140:143], v[176:179], v[126:129]
	v_mfma_f32_16x16x32_bf16 v[122:125], v[152:155], v[176:179], v[122:125]
	v_mfma_f32_16x16x32_bf16 v[110:113], v[140:143], v[184:187], v[110:113]
	v_mfma_f32_16x16x32_bf16 v[106:109], v[152:155], v[184:187], v[106:109]
	v_mfma_f32_16x16x32_bf16 v[94:97], v[140:143], v[202:205], v[94:97]
	v_mfma_f32_16x16x32_bf16 v[90:93], v[152:155], v[202:205], v[90:93]
	v_mfma_f32_16x16x32_bf16 v[78:81], v[140:143], v[210:213], v[78:81]
	v_mfma_f32_16x16x32_bf16 v[74:77], v[152:155], v[210:213], v[74:77]
	v_mfma_f32_16x16x32_bf16 v[126:129], v[148:151], v[180:183], v[126:129]
	v_mfma_f32_16x16x32_bf16 v[122:125], v[156:159], v[180:183], v[122:125]
	v_mfma_f32_16x16x32_bf16 v[110:113], v[148:151], v[188:191], v[110:113]
	v_mfma_f32_16x16x32_bf16 v[106:109], v[156:159], v[188:191], v[106:109]
	v_mfma_f32_16x16x32_bf16 v[94:97], v[148:151], v[206:209], v[94:97]
	v_mfma_f32_16x16x32_bf16 v[90:93], v[156:159], v[206:209], v[90:93]
	v_mfma_f32_16x16x32_bf16 v[78:81], v[148:151], v[214:217], v[78:81]
	v_mfma_f32_16x16x32_bf16 v[74:77], v[156:159], v[214:217], v[74:77]
	v_mfma_f32_16x16x32_bf16 v[118:121], v[160:163], v[176:179], v[118:121]
	v_mfma_f32_16x16x32_bf16 v[114:117], v[168:171], v[176:179], v[114:117]
	v_mfma_f32_16x16x32_bf16 v[102:105], v[160:163], v[184:187], v[102:105]
	v_mfma_f32_16x16x32_bf16 v[98:101], v[168:171], v[184:187], v[98:101]
	v_mfma_f32_16x16x32_bf16 v[86:89], v[160:163], v[202:205], v[86:89]
	v_mfma_f32_16x16x32_bf16 v[82:85], v[168:171], v[202:205], v[82:85]
	v_mfma_f32_16x16x32_bf16 v[70:73], v[160:163], v[210:213], v[70:73]
	v_mfma_f32_16x16x32_bf16 v[66:69], v[168:171], v[210:213], v[66:69]
	v_mfma_f32_16x16x32_bf16 v[118:121], v[164:167], v[180:183], v[118:121]
	v_mfma_f32_16x16x32_bf16 v[114:117], v[172:175], v[180:183], v[114:117]
	v_mfma_f32_16x16x32_bf16 v[102:105], v[164:167], v[188:191], v[102:105]
	v_mfma_f32_16x16x32_bf16 v[98:101], v[172:175], v[188:191], v[98:101]
	v_mfma_f32_16x16x32_bf16 v[86:89], v[164:167], v[206:209], v[86:89]
	v_mfma_f32_16x16x32_bf16 v[82:85], v[172:175], v[206:209], v[82:85]
	v_mfma_f32_16x16x32_bf16 v[70:73], v[164:167], v[214:217], v[70:73]
	v_mfma_f32_16x16x32_bf16 v[66:69], v[172:175], v[214:217], v[66:69]
	s_barrier
	s_add_i32 s51, s51, s36
	v_lshl_add_u64 v[192:193], s[22:23], 0, v[194:195]
	s_mov_b32 m0, s51
	ds_read_b128 v[176:179], v147 offset:16384
	ds_read_b128 v[180:183], v147 offset:17408
	ds_read_b128 v[184:187], v147 offset:18432
	ds_read_b128 v[188:191], v147 offset:19456
	ds_read_b128 v[202:205], v147 offset:20480
	ds_read_b128 v[206:209], v147 offset:21504
	ds_read_b128 v[210:213], v147 offset:22528
	ds_read_b128 v[214:217], v147 offset:23552
	global_load_lds_dwordx4 v[192:193], off
	s_add_i32 m0, s51, 0x2000
	s_add_u32 s52, s22, 0x40000
	v_lshl_add_u64 v[218:219], s[22:23], 0, v[134:135]
	s_addc_u32 s53, s23, 0
	s_add_i32 s51, s54, s36
	global_load_lds_dwordx4 v[218:219], off
	v_lshl_add_u64 v[220:221], s[52:53], 0, v[194:195]
	s_mov_b32 m0, s51
	v_lshl_add_u64 v[222:223], s[24:25], 0, v[132:133]
	global_load_lds_dwordx4 v[220:221], off
	v_lshl_add_u64 v[220:221], s[52:53], 0, v[134:135]
	s_add_i32 m0, s51, 0x2000
	s_nop 0
	global_load_lds_dwordx4 v[220:221], off
	v_lshl_add_u64 v[220:221], s[24:25], 0, v[130:131]
	s_mov_b32 m0, s19
	s_nop 0
	global_load_lds_dwordx4 v[220:221], off
	s_mov_b32 m0, s37
	s_nop 0
	global_load_lds_dwordx4 v[222:223], off
	s_waitcnt vmcnt(8)
	s_waitcnt lgkmcnt(0)
	s_barrier
	v_mfma_f32_16x16x32_bf16 v[62:65], v[140:143], v[176:179], v[62:65]
	v_mfma_f32_16x16x32_bf16 v[58:61], v[152:155], v[176:179], v[58:61]
	v_mfma_f32_16x16x32_bf16 v[46:49], v[140:143], v[184:187], v[46:49]
	v_mfma_f32_16x16x32_bf16 v[42:45], v[152:155], v[184:187], v[42:45]
	v_mfma_f32_16x16x32_bf16 v[30:33], v[140:143], v[202:205], v[30:33]
	v_mfma_f32_16x16x32_bf16 v[26:29], v[152:155], v[202:205], v[26:29]
	v_mfma_f32_16x16x32_bf16 v[14:17], v[140:143], v[210:213], v[14:17]
	v_mfma_f32_16x16x32_bf16 v[10:13], v[152:155], v[210:213], v[10:13]
	v_mfma_f32_16x16x32_bf16 v[62:65], v[148:151], v[180:183], v[62:65]
	v_mfma_f32_16x16x32_bf16 v[58:61], v[156:159], v[180:183], v[58:61]
	v_mfma_f32_16x16x32_bf16 v[46:49], v[148:151], v[188:191], v[46:49]
	v_mfma_f32_16x16x32_bf16 v[42:45], v[156:159], v[188:191], v[42:45]
	v_mfma_f32_16x16x32_bf16 v[30:33], v[148:151], v[206:209], v[30:33]
	v_mfma_f32_16x16x32_bf16 v[26:29], v[156:159], v[206:209], v[26:29]
	v_mfma_f32_16x16x32_bf16 v[14:17], v[148:151], v[214:217], v[14:17]
	v_mfma_f32_16x16x32_bf16 v[10:13], v[156:159], v[214:217], v[10:13]
	v_mfma_f32_16x16x32_bf16 v[54:57], v[160:163], v[176:179], v[54:57]
	v_mfma_f32_16x16x32_bf16 v[50:53], v[168:171], v[176:179], v[50:53]
	v_mfma_f32_16x16x32_bf16 v[38:41], v[160:163], v[184:187], v[38:41]
	v_mfma_f32_16x16x32_bf16 v[34:37], v[168:171], v[184:187], v[34:37]
	v_mfma_f32_16x16x32_bf16 v[22:25], v[160:163], v[202:205], v[22:25]
	v_mfma_f32_16x16x32_bf16 v[18:21], v[168:171], v[202:205], v[18:21]
	v_mfma_f32_16x16x32_bf16 v[6:9], v[160:163], v[210:213], v[6:9]
	v_mfma_f32_16x16x32_bf16 v[2:5], v[168:171], v[210:213], v[2:5]
	v_mfma_f32_16x16x32_bf16 v[54:57], v[164:167], v[180:183], v[54:57]
	v_mfma_f32_16x16x32_bf16 v[50:53], v[172:175], v[180:183], v[50:53]
	v_mfma_f32_16x16x32_bf16 v[38:41], v[164:167], v[188:191], v[38:41]
	v_mfma_f32_16x16x32_bf16 v[34:37], v[172:175], v[188:191], v[34:37]
	v_mfma_f32_16x16x32_bf16 v[22:25], v[164:167], v[206:209], v[22:25]
	v_mfma_f32_16x16x32_bf16 v[18:21], v[172:175], v[206:209], v[18:21]
	v_mfma_f32_16x16x32_bf16 v[6:9], v[164:167], v[214:217], v[6:9]
	v_mfma_f32_16x16x32_bf16 v[2:5], v[172:175], v[214:217], v[2:5]
	s_barrier
	s_add_i32 s51, 0, 0x18000
	s_add_i32 s52, 0, 0x1c000
	v_add_u32_e32 v156, s51, v145
	v_add_u32_e32 v172, s52, v145
	ds_read_b128 v[140:143], v156
	ds_read_b128 v[148:151], v156 offset:1024
	ds_read_b128 v[152:155], v156 offset:2048
	ds_read_b128 v[156:159], v156 offset:3072
	ds_read_b128 v[160:163], v172
	ds_read_b128 v[164:167], v172 offset:1024
	ds_read_b128 v[168:171], v172 offset:2048
	ds_read_b128 v[172:175], v172 offset:3072
	s_add_u32 s24, s24, 0x40000
	s_addc_u32 s25, s25, 0
	s_mov_b32 m0, s38
	v_lshl_add_u64 v[224:225], s[24:25], 0, v[130:131]
	ds_read_b128 v[176:179], v147 offset:32768
	ds_read_b128 v[180:183], v147 offset:33792
	ds_read_b128 v[184:187], v147 offset:34816
	ds_read_b128 v[188:191], v147 offset:35840
	ds_read_b128 v[202:205], v147 offset:36864
	ds_read_b128 v[206:209], v147 offset:37888
	ds_read_b128 v[210:213], v147 offset:38912
	ds_read_b128 v[214:217], v147 offset:39936
	global_load_lds_dwordx4 v[224:225], off
	v_lshl_add_u64 v[224:225], s[24:25], 0, v[132:133]
	s_mov_b32 m0, s39
	s_nop 0
	global_load_lds_dwordx4 v[224:225], off
	s_waitcnt vmcnt(8)
	s_waitcnt lgkmcnt(0)
	s_barrier
	v_mfma_f32_16x16x32_bf16 v[126:129], v[140:143], v[176:179], v[126:129]
	v_mfma_f32_16x16x32_bf16 v[122:125], v[152:155], v[176:179], v[122:125]
	v_mfma_f32_16x16x32_bf16 v[110:113], v[140:143], v[184:187], v[110:113]
	v_mfma_f32_16x16x32_bf16 v[106:109], v[152:155], v[184:187], v[106:109]
	v_mfma_f32_16x16x32_bf16 v[94:97], v[140:143], v[202:205], v[94:97]
	v_mfma_f32_16x16x32_bf16 v[90:93], v[152:155], v[202:205], v[90:93]
	v_mfma_f32_16x16x32_bf16 v[78:81], v[140:143], v[210:213], v[78:81]
	v_mfma_f32_16x16x32_bf16 v[74:77], v[152:155], v[210:213], v[74:77]
	v_mfma_f32_16x16x32_bf16 v[126:129], v[148:151], v[180:183], v[126:129]
	v_mfma_f32_16x16x32_bf16 v[122:125], v[156:159], v[180:183], v[122:125]
	v_mfma_f32_16x16x32_bf16 v[110:113], v[148:151], v[188:191], v[110:113]
	v_mfma_f32_16x16x32_bf16 v[106:109], v[156:159], v[188:191], v[106:109]
	v_mfma_f32_16x16x32_bf16 v[94:97], v[148:151], v[206:209], v[94:97]
	v_mfma_f32_16x16x32_bf16 v[90:93], v[156:159], v[206:209], v[90:93]
	v_mfma_f32_16x16x32_bf16 v[78:81], v[148:151], v[214:217], v[78:81]
	v_mfma_f32_16x16x32_bf16 v[74:77], v[156:159], v[214:217], v[74:77]
	v_mfma_f32_16x16x32_bf16 v[118:121], v[160:163], v[176:179], v[118:121]
	v_mfma_f32_16x16x32_bf16 v[114:117], v[168:171], v[176:179], v[114:117]
	v_mfma_f32_16x16x32_bf16 v[102:105], v[160:163], v[184:187], v[102:105]
	v_mfma_f32_16x16x32_bf16 v[98:101], v[168:171], v[184:187], v[98:101]
	v_mfma_f32_16x16x32_bf16 v[86:89], v[160:163], v[202:205], v[86:89]
	v_mfma_f32_16x16x32_bf16 v[82:85], v[168:171], v[202:205], v[82:85]
	v_mfma_f32_16x16x32_bf16 v[70:73], v[160:163], v[210:213], v[70:73]
	v_mfma_f32_16x16x32_bf16 v[66:69], v[168:171], v[210:213], v[66:69]
	v_mfma_f32_16x16x32_bf16 v[118:121], v[164:167], v[180:183], v[118:121]
	v_mfma_f32_16x16x32_bf16 v[114:117], v[172:175], v[180:183], v[114:117]
	v_mfma_f32_16x16x32_bf16 v[102:105], v[164:167], v[188:191], v[102:105]
	v_mfma_f32_16x16x32_bf16 v[98:101], v[172:175], v[188:191], v[98:101]
	v_mfma_f32_16x16x32_bf16 v[86:89], v[164:167], v[206:209], v[86:89]
	v_mfma_f32_16x16x32_bf16 v[82:85], v[172:175], v[206:209], v[82:85]
	v_mfma_f32_16x16x32_bf16 v[70:73], v[164:167], v[214:217], v[70:73]
	v_mfma_f32_16x16x32_bf16 v[66:69], v[172:175], v[214:217], v[66:69]
	s_barrier
	s_add_i32 s24, s51, s36
	v_lshl_add_u64 v[192:193], v[192:193], 0, s[92:93]
	s_mov_b32 m0, s24
	ds_read_b128 v[176:179], v147 offset:49152
	ds_read_b128 v[180:183], v147 offset:50176
	ds_read_b128 v[184:187], v147 offset:51200
	ds_read_b128 v[188:191], v147 offset:52224
	ds_read_b128 v[202:205], v147 offset:53248
	ds_read_b128 v[206:209], v147 offset:54272
	ds_read_b128 v[210:213], v147 offset:55296
	ds_read_b128 v[214:217], v147 offset:56320
	global_load_lds_dwordx4 v[192:193], off
	s_add_i32 m0, s24, 0x2000
	s_add_u32 s22, s22, 0x40080
	v_lshl_add_u64 v[192:193], v[218:219], 0, s[92:93]
	s_addc_u32 s23, s23, 0
	s_add_i32 s24, s52, s36
	global_load_lds_dwordx4 v[192:193], off
	v_lshl_add_u64 v[192:193], s[22:23], 0, v[194:195]
	s_mov_b32 m0, s24
	s_nop 0
	global_load_lds_dwordx4 v[192:193], off
	v_lshl_add_u64 v[192:193], s[22:23], 0, v[134:135]
	s_add_i32 m0, s24, 0x2000
	s_nop 0
	global_load_lds_dwordx4 v[192:193], off
	v_lshl_add_u64 v[192:193], v[220:221], 0, s[92:93]
	s_mov_b32 m0, s42
	s_nop 0
	global_load_lds_dwordx4 v[192:193], off
	v_lshl_add_u64 v[192:193], v[222:223], 0, s[92:93]
	s_mov_b32 m0, s43
	s_nop 0
	global_load_lds_dwordx4 v[192:193], off
	s_waitcnt vmcnt(8)
	s_waitcnt lgkmcnt(0)
	s_barrier
	v_mfma_f32_16x16x32_bf16 v[62:65], v[140:143], v[176:179], v[62:65]
	v_mfma_f32_16x16x32_bf16 v[58:61], v[152:155], v[176:179], v[58:61]
	v_mfma_f32_16x16x32_bf16 v[46:49], v[140:143], v[184:187], v[46:49]
	v_mfma_f32_16x16x32_bf16 v[42:45], v[152:155], v[184:187], v[42:45]
	v_mfma_f32_16x16x32_bf16 v[30:33], v[140:143], v[202:205], v[30:33]
	v_mfma_f32_16x16x32_bf16 v[26:29], v[152:155], v[202:205], v[26:29]
	v_mfma_f32_16x16x32_bf16 v[14:17], v[140:143], v[210:213], v[14:17]
	v_mfma_f32_16x16x32_bf16 v[10:13], v[152:155], v[210:213], v[10:13]
	v_mfma_f32_16x16x32_bf16 v[62:65], v[148:151], v[180:183], v[62:65]
	v_mfma_f32_16x16x32_bf16 v[58:61], v[156:159], v[180:183], v[58:61]
	v_mfma_f32_16x16x32_bf16 v[46:49], v[148:151], v[188:191], v[46:49]
	v_mfma_f32_16x16x32_bf16 v[42:45], v[156:159], v[188:191], v[42:45]
	v_mfma_f32_16x16x32_bf16 v[30:33], v[148:151], v[206:209], v[30:33]
	v_mfma_f32_16x16x32_bf16 v[26:29], v[156:159], v[206:209], v[26:29]
	v_mfma_f32_16x16x32_bf16 v[14:17], v[148:151], v[214:217], v[14:17]
	v_mfma_f32_16x16x32_bf16 v[10:13], v[156:159], v[214:217], v[10:13]
	v_mfma_f32_16x16x32_bf16 v[54:57], v[160:163], v[176:179], v[54:57]
	v_mfma_f32_16x16x32_bf16 v[50:53], v[168:171], v[176:179], v[50:53]
	v_mfma_f32_16x16x32_bf16 v[38:41], v[160:163], v[184:187], v[38:41]
	v_mfma_f32_16x16x32_bf16 v[34:37], v[168:171], v[184:187], v[34:37]
	v_mfma_f32_16x16x32_bf16 v[22:25], v[160:163], v[202:205], v[22:25]
	v_mfma_f32_16x16x32_bf16 v[18:21], v[168:171], v[202:205], v[18:21]
	v_mfma_f32_16x16x32_bf16 v[6:9], v[160:163], v[210:213], v[6:9]
	v_mfma_f32_16x16x32_bf16 v[2:5], v[168:171], v[210:213], v[2:5]
	v_mfma_f32_16x16x32_bf16 v[54:57], v[164:167], v[180:183], v[54:57]
	v_mfma_f32_16x16x32_bf16 v[50:53], v[172:175], v[180:183], v[50:53]
	v_mfma_f32_16x16x32_bf16 v[38:41], v[164:167], v[188:191], v[38:41]
	v_mfma_f32_16x16x32_bf16 v[34:37], v[172:175], v[188:191], v[34:37]
	v_mfma_f32_16x16x32_bf16 v[22:25], v[164:167], v[206:209], v[22:25]
	v_mfma_f32_16x16x32_bf16 v[18:21], v[172:175], v[206:209], v[18:21]
	v_mfma_f32_16x16x32_bf16 v[6:9], v[164:167], v[214:217], v[6:9]
	v_mfma_f32_16x16x32_bf16 v[2:5], v[172:175], v[214:217], v[2:5]
	s_barrier
	s_add_i32 s50, s50, 2
	s_add_u32 s20, s20, 0x100
	s_addc_u32 s21, s21, 0
	s_add_u32 s48, s48, 0x100
	s_addc_u32 s49, s49, 0
	s_cmp_gt_u32 s50, 13
	s_cbranch_scc0 .LBB0_1040
	s_and_b64 vcc, exec, s[8:9]
	s_cbranch_vccz .LBB0_1043
	s_barrier

.LBB0_1130:
	s_add_u32 s28, s26, 0xfff00080
	s_addc_u32 s29, s27, -1
	s_add_i32 s56, 0, 0x10000
	s_cmp_eq_u32 s55, 60
	s_cselect_b32 s31, s7, s29
	s_cselect_b32 s30, s9, s28
	s_cselect_b32 s29, s19, s54
	s_cselect_b32 s28, s21, s53
	s_add_i32 s58, 0, 0x14000
	v_add_u32_e32 v152, s56, v167
	v_add_u32_e32 v164, s58, v167
	ds_read_b128 v[130:133], v152
	ds_read_b128 v[134:137], v152 offset:1024
	ds_read_b128 v[138:141], v152 offset:2048
	ds_read_b128 v[152:155], v152 offset:3072
	ds_read_b128 v[156:159], v164
	ds_read_b128 v[160:163], v164 offset:1024
	ds_read_b128 v[170:173], v164 offset:2048
	ds_read_b128 v[174:177], v164 offset:3072
	v_lshl_add_u64 v[164:165], s[26:27], 0, v[148:149]
	s_add_i32 m0, s44, 0xc000
	ds_read_b128 v[178:181], v169
	ds_read_b128 v[182:185], v169 offset:1024
	ds_read_b128 v[186:189], v169 offset:2048
	ds_read_b128 v[190:193], v169 offset:3072
	ds_read_b128 v[202:205], v169 offset:4096
	ds_read_b128 v[206:209], v169 offset:5120
	ds_read_b128 v[210:213], v169 offset:6144
	ds_read_b128 v[214:217], v169 offset:7168
	global_load_lds_dwordx4 v[164:165], off
	v_lshl_add_u64 v[164:165], s[26:27], 0, v[150:151]
	s_add_i32 m0, s44, 0xe000
	s_nop 0
	global_load_lds_dwordx4 v[164:165], off
	s_waitcnt vmcnt(8)
	s_waitcnt lgkmcnt(0)
	s_barrier
	v_mfma_f32_16x16x32_bf16 v[126:129], v[130:133], v[178:181], v[126:129]
	v_mfma_f32_16x16x32_bf16 v[122:125], v[138:141], v[178:181], v[122:125]
	v_mfma_f32_16x16x32_bf16 v[110:113], v[130:133], v[186:189], v[110:113]
	v_mfma_f32_16x16x32_bf16 v[106:109], v[138:141], v[186:189], v[106:109]
	v_mfma_f32_16x16x32_bf16 v[94:97], v[130:133], v[202:205], v[94:97]
	v_mfma_f32_16x16x32_bf16 v[90:93], v[138:141], v[202:205], v[90:93]
	v_mfma_f32_16x16x32_bf16 v[78:81], v[130:133], v[210:213], v[78:81]
	v_mfma_f32_16x16x32_bf16 v[74:77], v[138:141], v[210:213], v[74:77]
	v_mfma_f32_16x16x32_bf16 v[126:129], v[134:137], v[182:185], v[126:129]
	v_mfma_f32_16x16x32_bf16 v[122:125], v[152:155], v[182:185], v[122:125]
	v_mfma_f32_16x16x32_bf16 v[110:113], v[134:137], v[190:193], v[110:113]
	v_mfma_f32_16x16x32_bf16 v[106:109], v[152:155], v[190:193], v[106:109]
	v_mfma_f32_16x16x32_bf16 v[94:97], v[134:137], v[206:209], v[94:97]
	v_mfma_f32_16x16x32_bf16 v[90:93], v[152:155], v[206:209], v[90:93]
	v_mfma_f32_16x16x32_bf16 v[78:81], v[134:137], v[214:217], v[78:81]
	v_mfma_f32_16x16x32_bf16 v[74:77], v[152:155], v[214:217], v[74:77]
	v_mfma_f32_16x16x32_bf16 v[118:121], v[156:159], v[178:181], v[118:121]
	v_mfma_f32_16x16x32_bf16 v[114:117], v[170:173], v[178:181], v[114:117]
	v_mfma_f32_16x16x32_bf16 v[102:105], v[156:159], v[186:189], v[102:105]
	v_mfma_f32_16x16x32_bf16 v[98:101], v[170:173], v[186:189], v[98:101]
	v_mfma_f32_16x16x32_bf16 v[86:89], v[156:159], v[202:205], v[86:89]
	v_mfma_f32_16x16x32_bf16 v[82:85], v[170:173], v[202:205], v[82:85]
	v_mfma_f32_16x16x32_bf16 v[70:73], v[156:159], v[210:213], v[70:73]
	v_mfma_f32_16x16x32_bf16 v[66:69], v[170:173], v[210:213], v[66:69]
	v_mfma_f32_16x16x32_bf16 v[118:121], v[160:163], v[182:185], v[118:121]
	v_mfma_f32_16x16x32_bf16 v[114:117], v[174:177], v[182:185], v[114:117]
	v_mfma_f32_16x16x32_bf16 v[102:105], v[160:163], v[190:193], v[102:105]
	v_mfma_f32_16x16x32_bf16 v[98:101], v[174:177], v[190:193], v[98:101]
	v_mfma_f32_16x16x32_bf16 v[86:89], v[160:163], v[206:209], v[86:89]
	v_mfma_f32_16x16x32_bf16 v[82:85], v[174:177], v[206:209], v[82:85]
	v_mfma_f32_16x16x32_bf16 v[70:73], v[160:163], v[214:217], v[70:73]
	v_mfma_f32_16x16x32_bf16 v[66:69], v[174:177], v[214:217], v[66:69]
	s_barrier
	s_add_i32 s56, s56, s43
	v_lshl_add_u64 v[164:165], s[28:29], 0, v[194:195]
	s_mov_b32 m0, s56
	ds_read_b128 v[178:181], v169 offset:16384
	ds_read_b128 v[182:185], v169 offset:17408
	ds_read_b128 v[186:189], v169 offset:18432
	ds_read_b128 v[190:193], v169 offset:19456
	ds_read_b128 v[202:205], v169 offset:20480
	ds_read_b128 v[206:209], v169 offset:21504
	ds_read_b128 v[210:213], v169 offset:22528
	ds_read_b128 v[214:217], v169 offset:23552
	global_load_lds_dwordx4 v[164:165], off
	s_add_i32 m0, s56, 0x2000
	s_add_u32 s56, s28, 0x100000
	v_lshl_add_u64 v[218:219], s[28:29], 0, v[146:147]
	s_addc_u32 s57, s29, 0
	s_add_i32 s58, s58, s43
	global_load_lds_dwordx4 v[218:219], off
	v_lshl_add_u64 v[220:221], s[56:57], 0, v[194:195]
	s_mov_b32 m0, s58
	v_lshl_add_u64 v[222:223], s[30:31], 0, v[144:145]
	global_load_lds_dwordx4 v[220:221], off
	v_lshl_add_u64 v[220:221], s[56:57], 0, v[146:147]
	s_add_i32 m0, s58, 0x2000
	s_nop 0
	global_load_lds_dwordx4 v[220:221], off
	v_lshl_add_u64 v[220:221], s[30:31], 0, v[142:143]
	s_mov_b32 m0, s44
	s_nop 0
	global_load_lds_dwordx4 v[220:221], off
	s_mov_b32 m0, s45
	s_nop 0
	global_load_lds_dwordx4 v[222:223], off
	s_waitcnt vmcnt(8)
	s_waitcnt lgkmcnt(0)
	s_barrier
	v_mfma_f32_16x16x32_bf16 v[62:65], v[130:133], v[178:181], v[62:65]
	v_mfma_f32_16x16x32_bf16 v[58:61], v[138:141], v[178:181], v[58:61]
	v_mfma_f32_16x16x32_bf16 v[46:49], v[130:133], v[186:189], v[46:49]
	v_mfma_f32_16x16x32_bf16 v[42:45], v[138:141], v[186:189], v[42:45]
	v_mfma_f32_16x16x32_bf16 v[30:33], v[130:133], v[202:205], v[30:33]
	v_mfma_f32_16x16x32_bf16 v[26:29], v[138:141], v[202:205], v[26:29]
	v_mfma_f32_16x16x32_bf16 v[14:17], v[130:133], v[210:213], v[14:17]
	v_mfma_f32_16x16x32_bf16 v[10:13], v[138:141], v[210:213], v[10:13]
	v_mfma_f32_16x16x32_bf16 v[62:65], v[134:137], v[182:185], v[62:65]
	v_mfma_f32_16x16x32_bf16 v[58:61], v[152:155], v[182:185], v[58:61]
	v_mfma_f32_16x16x32_bf16 v[46:49], v[134:137], v[190:193], v[46:49]
	v_mfma_f32_16x16x32_bf16 v[42:45], v[152:155], v[190:193], v[42:45]
	v_mfma_f32_16x16x32_bf16 v[30:33], v[134:137], v[206:209], v[30:33]
	v_mfma_f32_16x16x32_bf16 v[26:29], v[152:155], v[206:209], v[26:29]
	v_mfma_f32_16x16x32_bf16 v[14:17], v[134:137], v[214:217], v[14:17]
	v_mfma_f32_16x16x32_bf16 v[10:13], v[152:155], v[214:217], v[10:13]
	v_mfma_f32_16x16x32_bf16 v[54:57], v[156:159], v[178:181], v[54:57]
	v_mfma_f32_16x16x32_bf16 v[50:53], v[170:173], v[178:181], v[50:53]
	v_mfma_f32_16x16x32_bf16 v[38:41], v[156:159], v[186:189], v[38:41]
	v_mfma_f32_16x16x32_bf16 v[34:37], v[170:173], v[186:189], v[34:37]
	v_mfma_f32_16x16x32_bf16 v[22:25], v[156:159], v[202:205], v[22:25]
	v_mfma_f32_16x16x32_bf16 v[18:21], v[170:173], v[202:205], v[18:21]
	v_mfma_f32_16x16x32_bf16 v[6:9], v[156:159], v[210:213], v[6:9]
	v_mfma_f32_16x16x32_bf16 v[2:5], v[170:173], v[210:213], v[2:5]
	v_mfma_f32_16x16x32_bf16 v[54:57], v[160:163], v[182:185], v[54:57]
	v_mfma_f32_16x16x32_bf16 v[50:53], v[174:177], v[182:185], v[50:53]
	v_mfma_f32_16x16x32_bf16 v[38:41], v[160:163], v[190:193], v[38:41]
	v_mfma_f32_16x16x32_bf16 v[34:37], v[174:177], v[190:193], v[34:37]
	v_mfma_f32_16x16x32_bf16 v[22:25], v[160:163], v[206:209], v[22:25]
	v_mfma_f32_16x16x32_bf16 v[18:21], v[174:177], v[206:209], v[18:21]
	v_mfma_f32_16x16x32_bf16 v[6:9], v[160:163], v[214:217], v[6:9]
	v_mfma_f32_16x16x32_bf16 v[2:5], v[174:177], v[214:217], v[2:5]
	s_barrier
	s_add_i32 s56, 0, 0x18000
	s_add_i32 s57, 0, 0x1c000
	v_add_u32_e32 v152, s56, v167
	v_add_u32_e32 v174, s57, v167
	ds_read_b128 v[130:133], v152
	ds_read_b128 v[134:137], v152 offset:1024
	ds_read_b128 v[138:141], v152 offset:2048
	ds_read_b128 v[152:155], v152 offset:3072
	ds_read_b128 v[156:159], v174
	ds_read_b128 v[160:163], v174 offset:1024
	ds_read_b128 v[170:173], v174 offset:2048
	ds_read_b128 v[174:177], v174 offset:3072
	s_add_u32 s30, s30, 0x100000
	s_addc_u32 s31, s31, 0
	s_mov_b32 m0, s46
	v_lshl_add_u64 v[224:225], s[30:31], 0, v[142:143]
	ds_read_b128 v[178:181], v169 offset:32768
	ds_read_b128 v[182:185], v169 offset:33792
	ds_read_b128 v[186:189], v169 offset:34816
	ds_read_b128 v[190:193], v169 offset:35840
	ds_read_b128 v[202:205], v169 offset:36864
	ds_read_b128 v[206:209], v169 offset:37888
	ds_read_b128 v[210:213], v169 offset:38912
	ds_read_b128 v[214:217], v169 offset:39936
	global_load_lds_dwordx4 v[224:225], off
	v_lshl_add_u64 v[224:225], s[30:31], 0, v[144:145]
	s_mov_b32 m0, s47
	s_nop 0
	global_load_lds_dwordx4 v[224:225], off
	s_waitcnt vmcnt(8)
	s_waitcnt lgkmcnt(0)
	s_barrier
	v_mfma_f32_16x16x32_bf16 v[126:129], v[130:133], v[178:181], v[126:129]
	v_mfma_f32_16x16x32_bf16 v[122:125], v[138:141], v[178:181], v[122:125]
	v_mfma_f32_16x16x32_bf16 v[110:113], v[130:133], v[186:189], v[110:113]
	v_mfma_f32_16x16x32_bf16 v[106:109], v[138:141], v[186:189], v[106:109]
	v_mfma_f32_16x16x32_bf16 v[94:97], v[130:133], v[202:205], v[94:97]
	v_mfma_f32_16x16x32_bf16 v[90:93], v[138:141], v[202:205], v[90:93]
	v_mfma_f32_16x16x32_bf16 v[78:81], v[130:133], v[210:213], v[78:81]
	v_mfma_f32_16x16x32_bf16 v[74:77], v[138:141], v[210:213], v[74:77]
	v_mfma_f32_16x16x32_bf16 v[126:129], v[134:137], v[182:185], v[126:129]
	v_mfma_f32_16x16x32_bf16 v[122:125], v[152:155], v[182:185], v[122:125]
	v_mfma_f32_16x16x32_bf16 v[110:113], v[134:137], v[190:193], v[110:113]
	v_mfma_f32_16x16x32_bf16 v[106:109], v[152:155], v[190:193], v[106:109]
	v_mfma_f32_16x16x32_bf16 v[94:97], v[134:137], v[206:209], v[94:97]
	v_mfma_f32_16x16x32_bf16 v[90:93], v[152:155], v[206:209], v[90:93]
	v_mfma_f32_16x16x32_bf16 v[78:81], v[134:137], v[214:217], v[78:81]
	v_mfma_f32_16x16x32_bf16 v[74:77], v[152:155], v[214:217], v[74:77]
	v_mfma_f32_16x16x32_bf16 v[118:121], v[156:159], v[178:181], v[118:121]
	v_mfma_f32_16x16x32_bf16 v[114:117], v[170:173], v[178:181], v[114:117]
	v_mfma_f32_16x16x32_bf16 v[102:105], v[156:159], v[186:189], v[102:105]
	v_mfma_f32_16x16x32_bf16 v[98:101], v[170:173], v[186:189], v[98:101]
	v_mfma_f32_16x16x32_bf16 v[86:89], v[156:159], v[202:205], v[86:89]
	v_mfma_f32_16x16x32_bf16 v[82:85], v[170:173], v[202:205], v[82:85]
	v_mfma_f32_16x16x32_bf16 v[70:73], v[156:159], v[210:213], v[70:73]
	v_mfma_f32_16x16x32_bf16 v[66:69], v[170:173], v[210:213], v[66:69]
	v_mfma_f32_16x16x32_bf16 v[118:121], v[160:163], v[182:185], v[118:121]
	v_mfma_f32_16x16x32_bf16 v[114:117], v[174:177], v[182:185], v[114:117]
	v_mfma_f32_16x16x32_bf16 v[102:105], v[160:163], v[190:193], v[102:105]
	v_mfma_f32_16x16x32_bf16 v[98:101], v[174:177], v[190:193], v[98:101]
	v_mfma_f32_16x16x32_bf16 v[86:89], v[160:163], v[206:209], v[86:89]
	v_mfma_f32_16x16x32_bf16 v[82:85], v[174:177], v[206:209], v[82:85]
	v_mfma_f32_16x16x32_bf16 v[70:73], v[160:163], v[214:217], v[70:73]
	v_mfma_f32_16x16x32_bf16 v[66:69], v[174:177], v[214:217], v[66:69]
	s_barrier
	s_add_i32 s30, s56, s43
	v_lshl_add_u64 v[164:165], v[164:165], 0, s[92:93]
	s_mov_b32 m0, s30
	ds_read_b128 v[178:181], v169 offset:49152
	ds_read_b128 v[182:185], v169 offset:50176
	ds_read_b128 v[186:189], v169 offset:51200
	ds_read_b128 v[190:193], v169 offset:52224
	ds_read_b128 v[202:205], v169 offset:53248
	ds_read_b128 v[206:209], v169 offset:54272
	ds_read_b128 v[210:213], v169 offset:55296
	ds_read_b128 v[214:217], v169 offset:56320
	global_load_lds_dwordx4 v[164:165], off
	s_add_i32 m0, s30, 0x2000
	s_add_u32 s28, s28, 0x100080
	v_lshl_add_u64 v[164:165], v[218:219], 0, s[92:93]
	s_addc_u32 s29, s29, 0
	s_add_i32 s30, s57, s43
	global_load_lds_dwordx4 v[164:165], off
	v_lshl_add_u64 v[164:165], s[28:29], 0, v[194:195]
	s_mov_b32 m0, s30
	s_nop 0
	global_load_lds_dwordx4 v[164:165], off
	v_lshl_add_u64 v[164:165], s[28:29], 0, v[146:147]
	s_add_i32 m0, s30, 0x2000
	s_nop 0
	global_load_lds_dwordx4 v[164:165], off
	v_lshl_add_u64 v[164:165], v[220:221], 0, s[92:93]
	s_mov_b32 m0, s49
	s_nop 0
	global_load_lds_dwordx4 v[164:165], off
	v_lshl_add_u64 v[164:165], v[222:223], 0, s[92:93]
	s_mov_b32 m0, s50
	s_nop 0
	global_load_lds_dwordx4 v[164:165], off
	s_waitcnt vmcnt(8)
	s_waitcnt lgkmcnt(0)
	s_barrier
	v_mfma_f32_16x16x32_bf16 v[62:65], v[130:133], v[178:181], v[62:65]
	v_mfma_f32_16x16x32_bf16 v[58:61], v[138:141], v[178:181], v[58:61]
	v_mfma_f32_16x16x32_bf16 v[46:49], v[130:133], v[186:189], v[46:49]
	v_mfma_f32_16x16x32_bf16 v[42:45], v[138:141], v[186:189], v[42:45]
	v_mfma_f32_16x16x32_bf16 v[30:33], v[130:133], v[202:205], v[30:33]
	v_mfma_f32_16x16x32_bf16 v[26:29], v[138:141], v[202:205], v[26:29]
	v_mfma_f32_16x16x32_bf16 v[14:17], v[130:133], v[210:213], v[14:17]
	v_mfma_f32_16x16x32_bf16 v[10:13], v[138:141], v[210:213], v[10:13]
	v_mfma_f32_16x16x32_bf16 v[62:65], v[134:137], v[182:185], v[62:65]
	v_mfma_f32_16x16x32_bf16 v[58:61], v[152:155], v[182:185], v[58:61]
	v_mfma_f32_16x16x32_bf16 v[46:49], v[134:137], v[190:193], v[46:49]
	v_mfma_f32_16x16x32_bf16 v[42:45], v[152:155], v[190:193], v[42:45]
	v_mfma_f32_16x16x32_bf16 v[30:33], v[134:137], v[206:209], v[30:33]
	v_mfma_f32_16x16x32_bf16 v[26:29], v[152:155], v[206:209], v[26:29]
	v_mfma_f32_16x16x32_bf16 v[14:17], v[134:137], v[214:217], v[14:17]
	v_mfma_f32_16x16x32_bf16 v[10:13], v[152:155], v[214:217], v[10:13]
	v_mfma_f32_16x16x32_bf16 v[54:57], v[156:159], v[178:181], v[54:57]
	v_mfma_f32_16x16x32_bf16 v[50:53], v[170:173], v[178:181], v[50:53]
	v_mfma_f32_16x16x32_bf16 v[38:41], v[156:159], v[186:189], v[38:41]
	v_mfma_f32_16x16x32_bf16 v[34:37], v[170:173], v[186:189], v[34:37]
	v_mfma_f32_16x16x32_bf16 v[22:25], v[156:159], v[202:205], v[22:25]
	v_mfma_f32_16x16x32_bf16 v[18:21], v[170:173], v[202:205], v[18:21]
	v_mfma_f32_16x16x32_bf16 v[6:9], v[156:159], v[210:213], v[6:9]
	v_mfma_f32_16x16x32_bf16 v[2:5], v[170:173], v[210:213], v[2:5]
	v_mfma_f32_16x16x32_bf16 v[54:57], v[160:163], v[182:185], v[54:57]
	v_mfma_f32_16x16x32_bf16 v[50:53], v[174:177], v[182:185], v[50:53]
	v_mfma_f32_16x16x32_bf16 v[38:41], v[160:163], v[190:193], v[38:41]
	v_mfma_f32_16x16x32_bf16 v[34:37], v[174:177], v[190:193], v[34:37]
	v_mfma_f32_16x16x32_bf16 v[22:25], v[160:163], v[206:209], v[22:25]
	v_mfma_f32_16x16x32_bf16 v[18:21], v[174:177], v[206:209], v[18:21]
	v_mfma_f32_16x16x32_bf16 v[6:9], v[160:163], v[214:217], v[6:9]
	v_mfma_f32_16x16x32_bf16 v[2:5], v[174:177], v[214:217], v[2:5]
	s_barrier
	s_add_i32 s55, s55, 2
	s_add_u32 s26, s26, 0x100
	s_addc_u32 s27, s27, 0
	s_add_u32 s53, s53, 0x100
	s_addc_u32 s54, s54, 0
	s_cmp_gt_u32 s55, 61
	s_cbranch_scc0 .LBB0_1130
	v_lshl_add_u32 v154, s6, 8, v166
	v_lshl_or_b32 v152, s8, 8, v168
	v_ashrrev_i32_e32 v155, 31, v154
	v_lshlrev_b64 v[130:131], 11, v[154:155]
	v_ashrrev_i32_e32 v153, 31, v152
	v_or_b32_e32 v156, 16, v154
	v_lshl_add_u64 v[130:131], s[12:13], 0, v[130:131]
	v_lshlrev_b64 v[132:133], 1, v[152:153]
	v_ashrrev_i32_e32 v157, 31, v156
	v_lshl_add_u64 v[160:161], v[130:131], 0, v[132:133]
	v_lshlrev_b64 v[130:131], 11, v[156:157]
	global_load_dwordx4 v[170:173], v[160:161], off
	global_load_dwordx4 v[138:141], v[160:161], off offset:256
	v_lshl_add_u64 v[130:131], s[12:13], 0, v[130:131]
	v_lshl_add_u64 v[158:159], v[130:131], 0, v[132:133]
	global_load_dwordx4 v[134:137], v[158:159], off
	global_load_dwordx4 v[130:133], v[158:159], off offset:256
	v_cndmask_b32_e64 v162, 0, 1, s[16:17]
	v_cmp_ne_u32_e64 s[6:7], 1, v162
	v_lshlrev_b64 v[162:163], 10, v[154:155]
	v_lshl_add_u64 v[162:163], v[162:163], 0, v[152:153]
	s_andn2_b64 vcc, exec, s[16:17]
	s_waitcnt vmcnt(0)
	v_lshlrev_b32_e32 v164, 16, v170
	v_and_b32_e32 v165, 0xffff0000, v170
	v_lshlrev_b32_e32 v170, 16, v171
	v_and_b32_e32 v171, 0xffff0000, v171
	v_lshlrev_b32_e32 v174, 16, v172
	v_and_b32_e32 v175, 0xffff0000, v172
	v_lshlrev_b32_e32 v172, 16, v173
	v_and_b32_e32 v173, 0xffff0000, v173
	v_pk_add_f32 v[126:127], v[126:127], v[164:165]
	v_pk_add_f32 v[128:129], v[128:129], v[170:171]
	v_pk_add_f32 v[122:123], v[122:123], v[174:175]
	v_pk_add_f32 v[124:125], v[124:125], v[172:173]
	v_lshl_add_u64 v[164:165], v[162:163], 2, s[14:15]
	s_cbranch_vccnz .LBB0_1210
	global_store_dwordx4 v[164:165], v[126:129], off
	global_store_dwordx4 v[164:165], v[122:125], off offset:16
	s_cbranch_execnz .LBB0_1134
